# v59 + nt hint on the 48 single-use Y (f32 GEMM output) row loads of the norm phases P3/P7/P11/P14
# baseline (speedup 1.0000x reference)
.LBB0_580:
	s_mov_b32 s4, 4
	s_ashr_i32 s5, s4, 31
	s_lshl_b64 s[4:5], s[4:5], 3
	s_add_u32 s4, s70, s4
	s_addc_u32 s5, s71, s5
	v_mov_b32_e32 v4, v0
	s_load_dwordx2 s[4:5], s[4:5], 0x0
	s_add_u32 s44, s72, s18
	v_and_b32_e32 v68, 63, v4
	v_lshlrev_b32_e32 v2, 2, v68
	s_addc_u32 s45, s73, s19
	global_load_dword v2, v2, s[44:45]
	v_cmp_lt_i32_e32 vcc, v61, v60
	s_add_u32 s44, s72, s6
	v_lshlrev_b32_e32 v14, 3, v68
	s_waitcnt lgkmcnt(0)
	v_cndmask_b32_e32 v3, v17, v61, vcc
	v_lshlrev_b32_e32 v72, 2, v3
	v_cmp_lt_i32_e32 vcc, v62, v60
	s_addc_u32 s45, s73, s7
	v_lshlrev_b32_e32 v5, 16, v4
	v_and_b32_e32 v4, 15, v4
	v_lshlrev_b32_e32 v4, 3, v4
	v_and_or_b32 v4, v5, s43, v4
	v_mov_b32_e32 v5, v15
	s_waitcnt vmcnt(0)
	ds_bpermute_b32 v3, v72, v2
	s_waitcnt lgkmcnt(0)
	v_add_f32_e32 v2, v2, v3
	v_cndmask_b32_e32 v3, v17, v62, vcc
	v_lshlrev_b32_e32 v73, 2, v3
	ds_bpermute_b32 v3, v73, v2
	v_cmp_lt_i32_e32 vcc, v63, v60
	s_waitcnt lgkmcnt(0)
	v_add_f32_e32 v2, v2, v3
	v_cndmask_b32_e32 v3, v17, v63, vcc
	v_lshlrev_b32_e32 v74, 2, v3
	ds_bpermute_b32 v3, v74, v2
	v_cmp_lt_i32_e32 vcc, v64, v60
	s_waitcnt lgkmcnt(0)
	v_add_f32_e32 v2, v2, v3
	v_cndmask_b32_e32 v3, v17, v64, vcc
	v_lshlrev_b32_e32 v71, 2, v3
	ds_bpermute_b32 v3, v71, v2
	v_cmp_lt_i32_e32 vcc, v65, v60
	s_waitcnt lgkmcnt(0)
	v_add_f32_e32 v2, v2, v3
	v_cndmask_b32_e32 v3, v17, v65, vcc
	v_lshlrev_b32_e32 v70, 2, v3
	ds_bpermute_b32 v3, v70, v2
	v_cmp_lt_i32_e32 vcc, v66, v60
	s_waitcnt lgkmcnt(0)
	v_add_f32_e32 v2, v2, v3
	v_cndmask_b32_e32 v3, v17, v66, vcc
	v_lshlrev_b32_e32 v69, 2, v3
	ds_bpermute_b32 v3, v69, v2
	s_waitcnt lgkmcnt(0)
	v_add_f32_e32 v2, v2, v3
	v_fmamk_f32 v2, v2, 0x39800000, v67
	v_rsq_f32_e32 v2, v2
	s_nop 0
	v_mul_f32_e32 v16, 0.5, v2
	v_lshl_add_u64 v[2:3], s[44:45], 0, v[14:15]
	s_add_u32 s44, s72, s12
	s_addc_u32 s45, s73, s13
	v_lshl_add_u64 v[18:19], s[44:45], 0, v[4:5]
	v_add_co_u32_e32 v46, vcc, s20, v18
	v_lshlrev_b32_e32 v14, 4, v68
	s_nop 0
	v_addc_co_u32_e32 v47, vcc, 0, v19, vcc
	v_add_co_u32_e32 v28, vcc, s21, v2
	global_load_dwordx2 v[22:23], v[46:47], off
	s_nop 0
	v_addc_co_u32_e32 v29, vcc, 0, v3, vcc
	v_add_co_u32_e32 v20, vcc, s31, v2
	v_lshl_add_u64 v[26:27], s[4:5], 0, v[14:15]
	s_nop 0
	v_addc_co_u32_e32 v21, vcc, 0, v3, vcc
	global_load_dwordx2 v[24:25], v[20:21], off offset:-4096
	global_load_dwordx4 v[48:51], v14, s[4:5]
	v_add_co_u32_e32 v40, vcc, s22, v18
	s_waitcnt vmcnt(2)
	v_lshlrev_b32_e32 v56, 16, v22
	v_addc_co_u32_e32 v41, vcc, 0, v19, vcc
	global_load_dwordx2 v[42:43], v[40:41], off
	global_load_dwordx2 v[52:53], v[28:29], off offset:512
	global_load_dwordx4 v[10:13], v14, s[4:5] offset:1024
	v_add_co_u32_e32 v30, vcc, s23, v18
	v_and_b32_e32 v57, 0xffff0000, v22
	s_nop 0
	v_addc_co_u32_e32 v31, vcc, 0, v19, vcc
	global_load_dwordx2 v[38:39], v[30:31], off
	global_load_dwordx2 v[44:45], v[28:29], off offset:1024
	global_load_dwordx4 v[2:5], v14, s[4:5] offset:2048
	v_add_co_u32_e32 v32, vcc, s24, v18
	s_waitcnt vmcnt(7)
	v_lshlrev_b32_e32 v54, 16, v24
	v_addc_co_u32_e32 v33, vcc, 0, v19, vcc
	global_load_dwordx2 v[34:35], v[32:33], off
	global_load_dwordx2 v[36:37], v[28:29], off offset:1536
	global_load_dwordx4 v[6:9], v14, s[4:5] offset:3072
	v_and_b32_e32 v55, 0xffff0000, v24
	v_lshlrev_b32_e32 v24, 16, v25
	v_and_b32_e32 v25, 0xffff0000, v25
	v_lshlrev_b32_e32 v22, 16, v23
	v_and_b32_e32 v23, 0xffff0000, v23
	v_pk_mul_f32 v[54:55], v[16:17], v[54:55] op_sel_hi:[0,1]
	v_pk_mul_f32 v[24:25], v[16:17], v[24:25] op_sel_hi:[0,1]
	s_waitcnt vmcnt(9)
	v_pk_fma_f32 v[22:23], v[50:51], v[24:25], v[22:23]
	v_pk_fma_f32 v[24:25], v[48:49], v[54:55], v[56:57]
	s_waitcnt vmcnt(8)
	v_lshlrev_b32_e32 v50, 16, v42
	v_cvt_pk_bf16_f32 v48, v24, v25
	v_cvt_pk_bf16_f32 v49, v22, v23
	global_store_dwordx2 v[46:47], v[48:49], off
	s_waitcnt vmcnt(8)
	v_lshlrev_b32_e32 v46, 16, v52
	v_and_b32_e32 v47, 0xffff0000, v52
	v_lshlrev_b32_e32 v48, 16, v53
	v_and_b32_e32 v49, 0xffff0000, v53
	v_and_b32_e32 v51, 0xffff0000, v42
	v_lshlrev_b32_e32 v42, 16, v43
	v_and_b32_e32 v43, 0xffff0000, v43
	v_pk_mul_f32 v[46:47], v[16:17], v[46:47] op_sel_hi:[0,1]
	v_pk_mul_f32 v[48:49], v[16:17], v[48:49] op_sel_hi:[0,1]
	s_waitcnt vmcnt(7)
	v_pk_fma_f32 v[12:13], v[12:13], v[48:49], v[42:43]
	v_pk_fma_f32 v[10:11], v[10:11], v[46:47], v[50:51]
	v_mul_f32_e32 v14, v25, v25
	v_cvt_pk_bf16_f32 v42, v10, v11
	v_cvt_pk_bf16_f32 v43, v12, v13
	global_store_dwordx2 v[40:41], v[42:43], off
	s_waitcnt vmcnt(6)
	v_lshlrev_b32_e32 v40, 16, v44
	v_and_b32_e32 v41, 0xffff0000, v44
	v_lshlrev_b32_e32 v42, 16, v45
	v_and_b32_e32 v43, 0xffff0000, v45
	v_lshlrev_b32_e32 v44, 16, v38
	v_and_b32_e32 v45, 0xffff0000, v38
	v_lshlrev_b32_e32 v38, 16, v39
	v_and_b32_e32 v39, 0xffff0000, v39
	v_pk_mul_f32 v[40:41], v[16:17], v[40:41] op_sel_hi:[0,1]
	v_pk_mul_f32 v[42:43], v[16:17], v[42:43] op_sel_hi:[0,1]
	s_waitcnt vmcnt(5)
	v_pk_fma_f32 v[4:5], v[4:5], v[42:43], v[38:39]
	v_pk_fma_f32 v[2:3], v[2:3], v[40:41], v[44:45]
	v_mul_f32_e32 v11, v11, v11
	v_cvt_pk_bf16_f32 v38, v2, v3
	v_cvt_pk_bf16_f32 v39, v4, v5
	global_store_dwordx2 v[30:31], v[38:39], off
	s_waitcnt vmcnt(4)
	v_lshlrev_b32_e32 v30, 16, v36
	v_and_b32_e32 v31, 0xffff0000, v36
	v_lshlrev_b32_e32 v36, 16, v37
	v_and_b32_e32 v37, 0xffff0000, v37
	v_lshlrev_b32_e32 v38, 16, v34
	v_and_b32_e32 v39, 0xffff0000, v34
	v_lshlrev_b32_e32 v34, 16, v35
	v_and_b32_e32 v35, 0xffff0000, v35
	v_pk_mul_f32 v[36:37], v[16:17], v[36:37] op_sel_hi:[0,1]
	s_waitcnt vmcnt(3)
	v_pk_fma_f32 v[8:9], v[8:9], v[36:37], v[34:35]
	v_add_co_u32_e32 v34, vcc, s25, v18
	v_pk_mul_f32 v[30:31], v[16:17], v[30:31] op_sel_hi:[0,1]
	s_nop 0
	v_addc_co_u32_e32 v35, vcc, 0, v19, vcc
	v_pk_fma_f32 v[6:7], v[6:7], v[30:31], v[38:39]
	v_add_co_u32_e32 v54, vcc, s26, v26
	v_cvt_pk_bf16_f32 v30, v6, v7
	v_cvt_pk_bf16_f32 v31, v8, v9
	global_store_dwordx2 v[32:33], v[30:31], off
	s_nop 0
	v_addc_co_u32_e32 v55, vcc, 0, v27, vcc
	global_load_dwordx2 v[38:39], v[34:35], off
	global_load_dwordx2 v[42:43], v[28:29], off offset:2048
	v_add_co_u32_e32 v44, vcc, s33, v26
	v_mul_f32_e32 v3, v3, v3
	s_nop 0
	v_addc_co_u32_e32 v45, vcc, 0, v27, vcc
	global_load_dwordx4 v[30:33], v[44:45], off offset:-4096 nt
	v_add_co_u32_e32 v58, vcc, s27, v18
	v_fmac_f32_e32 v11, v10, v10
	s_nop 0
	v_addc_co_u32_e32 v59, vcc, 0, v19, vcc
	global_load_dwordx2 v[76:77], v[58:59], off
	global_load_dwordx2 v[78:79], v[28:29], off offset:2560
	global_load_dwordx4 v[46:49], v[54:55], off offset:1024 nt
	v_add_co_u32_e32 v40, vcc, s28, v18
	v_mul_f32_e32 v10, v13, v13
	s_nop 0
	v_addc_co_u32_e32 v41, vcc, 0, v19, vcc
	global_load_dwordx2 v[36:37], v[40:41], off
	global_load_dwordx2 v[80:81], v[28:29], off offset:3072
	global_load_dwordx4 v[50:53], v[54:55], off offset:2048 nt
	v_add_co_u32_e32 v82, vcc, s29, v18
	v_fmac_f32_e32 v3, v2, v2
	s_nop 0
	v_addc_co_u32_e32 v83, vcc, 0, v19, vcc
	global_load_dwordx2 v[84:85], v[82:83], off
	global_load_dwordx2 v[86:87], v[28:29], off offset:3584
	s_nop 0
	global_load_dwordx4 v[54:57], v[54:55], off offset:3072 nt
	v_mul_f32_e32 v2, v5, v5
	v_fmac_f32_e32 v14, v24, v24
	v_fmac_f32_e32 v10, v12, v12
	v_fmac_f32_e32 v2, v4, v4
	v_add_f32_e32 v10, v11, v10
	v_add_f32_e32 v2, v3, v2
	v_mul_f32_e32 v3, v7, v7
	v_mul_f32_e32 v4, v9, v9
	v_fmac_f32_e32 v3, v6, v6
	v_fmac_f32_e32 v4, v8, v8
	v_add_f32_e32 v3, v3, v4
	s_waitcnt vmcnt(11)
	v_lshlrev_b32_e32 v88, 16, v38
	s_waitcnt vmcnt(10)
	v_lshlrev_b32_e32 v28, 16, v42
	v_and_b32_e32 v29, 0xffff0000, v42
	v_lshlrev_b32_e32 v42, 16, v43
	v_and_b32_e32 v43, 0xffff0000, v43
	v_and_b32_e32 v89, 0xffff0000, v38
	v_lshlrev_b32_e32 v38, 16, v39
	v_and_b32_e32 v39, 0xffff0000, v39
	v_pk_mul_f32 v[90:91], v[16:17], v[28:29] op_sel_hi:[0,1]
	v_pk_mul_f32 v[28:29], v[16:17], v[42:43] op_sel_hi:[0,1]
	s_waitcnt vmcnt(9)
	v_pk_fma_f32 v[28:29], v[32:33], v[28:29], v[38:39]
	v_pk_fma_f32 v[30:31], v[30:31], v[90:91], v[88:89]
	s_waitcnt vmcnt(8)
	v_lshlrev_b32_e32 v38, 16, v76
	v_cvt_pk_bf16_f32 v32, v30, v31
	v_cvt_pk_bf16_f32 v33, v28, v29
	global_store_dwordx2 v[34:35], v[32:33], off
	s_waitcnt vmcnt(8)
	v_lshlrev_b32_e32 v32, 16, v78
	v_and_b32_e32 v33, 0xffff0000, v78
	v_lshlrev_b32_e32 v34, 16, v79
	v_and_b32_e32 v35, 0xffff0000, v79
	v_and_b32_e32 v39, 0xffff0000, v76
	v_lshlrev_b32_e32 v42, 16, v77
	v_and_b32_e32 v43, 0xffff0000, v77
	v_pk_mul_f32 v[76:77], v[16:17], v[32:33] op_sel_hi:[0,1]
	v_pk_mul_f32 v[32:33], v[16:17], v[34:35] op_sel_hi:[0,1]
	s_waitcnt vmcnt(7)
	v_pk_fma_f32 v[32:33], v[48:49], v[32:33], v[42:43]
	v_pk_fma_f32 v[34:35], v[46:47], v[76:77], v[38:39]
	s_waitcnt vmcnt(5)
	v_lshlrev_b32_e32 v42, 16, v81
	v_cvt_pk_bf16_f32 v38, v34, v35
	v_cvt_pk_bf16_f32 v39, v32, v33
	global_store_dwordx2 v[58:59], v[38:39], off
	v_lshlrev_b32_e32 v38, 16, v80
	v_and_b32_e32 v39, 0xffff0000, v80
	v_and_b32_e32 v43, 0xffff0000, v81
	v_lshlrev_b32_e32 v46, 16, v36
	v_and_b32_e32 v47, 0xffff0000, v36
	v_lshlrev_b32_e32 v36, 16, v37
	v_and_b32_e32 v37, 0xffff0000, v37
	v_pk_mul_f32 v[38:39], v[16:17], v[38:39] op_sel_hi:[0,1]
	v_pk_mul_f32 v[42:43], v[16:17], v[42:43] op_sel_hi:[0,1]
	s_waitcnt vmcnt(5)
	v_pk_fma_f32 v[36:37], v[52:53], v[42:43], v[36:37]
	v_pk_fma_f32 v[38:39], v[50:51], v[38:39], v[46:47]
	s_waitcnt vmcnt(4)
	v_lshlrev_b32_e32 v46, 16, v84
	v_cvt_pk_bf16_f32 v42, v38, v39
	v_cvt_pk_bf16_f32 v43, v36, v37
	global_store_dwordx2 v[40:41], v[42:43], off
	s_waitcnt vmcnt(4)
	v_lshlrev_b32_e32 v40, 16, v86
	v_and_b32_e32 v41, 0xffff0000, v86
	v_lshlrev_b32_e32 v42, 16, v87
	v_and_b32_e32 v43, 0xffff0000, v87
	v_and_b32_e32 v47, 0xffff0000, v84
	v_lshlrev_b32_e32 v48, 16, v85
	v_and_b32_e32 v49, 0xffff0000, v85
	v_pk_mul_f32 v[50:51], v[16:17], v[40:41] op_sel_hi:[0,1]
	v_pk_mul_f32 v[40:41], v[16:17], v[42:43] op_sel_hi:[0,1]
	s_waitcnt vmcnt(3)
	v_pk_fma_f32 v[40:41], v[56:57], v[40:41], v[48:49]
	v_pk_fma_f32 v[42:43], v[54:55], v[50:51], v[46:47]
	v_add_co_u32_e32 v54, vcc, s30, v18
	v_cvt_pk_bf16_f32 v46, v42, v43
	v_cvt_pk_bf16_f32 v47, v40, v41
	global_store_dwordx2 v[82:83], v[46:47], off
	s_nop 0
	v_addc_co_u32_e32 v55, vcc, 0, v19, vcc
	global_load_dwordx2 v[58:59], v[54:55], off
	global_load_dwordx2 v[84:85], v[20:21], off
	global_load_dwordx4 v[46:49], v[44:45], off nt
	v_add_co_u32_e32 v86, vcc, s34, v18
	v_mul_f32_e32 v4, v29, v29
	s_nop 0
	v_addc_co_u32_e32 v87, vcc, 0, v19, vcc
	global_load_dwordx2 v[88:89], v[86:87], off
	global_load_dwordx2 v[90:91], v[20:21], off offset:512
	global_load_dwordx4 v[50:53], v[44:45], off offset:1024 nt
	v_add_co_u32_e32 v56, vcc, s35, v18
	v_fmac_f32_e32 v4, v28, v28
	s_nop 0
	v_addc_co_u32_e32 v57, vcc, 0, v19, vcc
	global_load_dwordx2 v[92:93], v[56:57], off
	global_load_dwordx2 v[94:95], v[20:21], off offset:1024
	global_load_dwordx4 v[76:79], v[44:45], off offset:2048 nt
	v_add_co_u32_e32 v96, vcc, s36, v18
	s_waitcnt vmcnt(8)
	v_lshlrev_b32_e32 v102, 16, v58
	v_addc_co_u32_e32 v97, vcc, 0, v19, vcc
	global_load_dwordx2 v[98:99], v[96:97], off
	global_load_dwordx2 v[100:101], v[20:21], off offset:1536
	global_load_dwordx4 v[80:83], v[44:45], off offset:3072 nt
	s_waitcnt vmcnt(10)
	v_lshlrev_b32_e32 v44, 16, v84
	v_and_b32_e32 v45, 0xffff0000, v84
	v_lshlrev_b32_e32 v84, 16, v85
	v_and_b32_e32 v85, 0xffff0000, v85
	v_and_b32_e32 v103, 0xffff0000, v58
	v_lshlrev_b32_e32 v58, 16, v59
	v_and_b32_e32 v59, 0xffff0000, v59
	v_pk_mul_f32 v[104:105], v[16:17], v[44:45] op_sel_hi:[0,1]
	v_pk_mul_f32 v[44:45], v[16:17], v[84:85] op_sel_hi:[0,1]
	s_waitcnt vmcnt(9)
	v_pk_fma_f32 v[44:45], v[48:49], v[44:45], v[58:59]
	v_pk_fma_f32 v[46:47], v[46:47], v[104:105], v[102:103]
	s_waitcnt vmcnt(8)
	v_lshlrev_b32_e32 v58, 16, v88
	v_cvt_pk_bf16_f32 v48, v46, v47
	v_cvt_pk_bf16_f32 v49, v44, v45
	global_store_dwordx2 v[54:55], v[48:49], off
	s_waitcnt vmcnt(8)
	v_lshlrev_b32_e32 v48, 16, v90
	v_and_b32_e32 v49, 0xffff0000, v90
	v_lshlrev_b32_e32 v54, 16, v91
	v_and_b32_e32 v55, 0xffff0000, v91
	v_and_b32_e32 v59, 0xffff0000, v88
	v_lshlrev_b32_e32 v84, 16, v89
	v_and_b32_e32 v85, 0xffff0000, v89
	v_pk_mul_f32 v[88:89], v[16:17], v[48:49] op_sel_hi:[0,1]
	v_pk_mul_f32 v[48:49], v[16:17], v[54:55] op_sel_hi:[0,1]
	s_waitcnt vmcnt(7)
	v_pk_fma_f32 v[48:49], v[52:53], v[48:49], v[84:85]
	v_pk_fma_f32 v[50:51], v[50:51], v[88:89], v[58:59]
	s_waitcnt vmcnt(5)
	v_lshlrev_b32_e32 v54, 16, v95
	v_cvt_pk_bf16_f32 v52, v50, v51
	v_cvt_pk_bf16_f32 v53, v48, v49
	global_store_dwordx2 v[86:87], v[52:53], off
	v_lshlrev_b32_e32 v52, 16, v94
	v_and_b32_e32 v53, 0xffff0000, v94
	v_and_b32_e32 v55, 0xffff0000, v95
	v_lshlrev_b32_e32 v58, 16, v92
	v_and_b32_e32 v59, 0xffff0000, v92
	v_lshlrev_b32_e32 v84, 16, v93
	v_and_b32_e32 v85, 0xffff0000, v93
	v_pk_mul_f32 v[86:87], v[16:17], v[52:53] op_sel_hi:[0,1]
	v_pk_mul_f32 v[52:53], v[16:17], v[54:55] op_sel_hi:[0,1]
	s_waitcnt vmcnt(5)
	v_pk_fma_f32 v[52:53], v[78:79], v[52:53], v[84:85]
	v_pk_fma_f32 v[54:55], v[76:77], v[86:87], v[58:59]
	v_add_co_u32_e32 v92, vcc, s37, v18
	v_cvt_pk_bf16_f32 v58, v54, v55
	v_cvt_pk_bf16_f32 v59, v52, v53
	global_store_dwordx2 v[56:57], v[58:59], off
	s_nop 0
	v_addc_co_u32_e32 v93, vcc, 0, v19, vcc
	v_add_co_u32_e32 v26, vcc, s38, v26
	s_waitcnt vmcnt(5)
	v_lshlrev_b32_e32 v76, 16, v98
	s_waitcnt vmcnt(4)
	v_lshlrev_b32_e32 v56, 16, v100
	v_and_b32_e32 v57, 0xffff0000, v100
	v_lshlrev_b32_e32 v58, 16, v101
	v_and_b32_e32 v59, 0xffff0000, v101
	v_and_b32_e32 v77, 0xffff0000, v98
	v_lshlrev_b32_e32 v78, 16, v99
	v_and_b32_e32 v79, 0xffff0000, v99
	v_pk_mul_f32 v[84:85], v[16:17], v[56:57] op_sel_hi:[0,1]
	v_pk_mul_f32 v[56:57], v[16:17], v[58:59] op_sel_hi:[0,1]
	s_waitcnt vmcnt(3)
	v_pk_fma_f32 v[56:57], v[82:83], v[56:57], v[78:79]
	v_pk_fma_f32 v[58:59], v[80:81], v[84:85], v[76:77]
	v_addc_co_u32_e32 v27, vcc, 0, v27, vcc
	v_cvt_pk_bf16_f32 v76, v58, v59
	v_cvt_pk_bf16_f32 v77, v56, v57
	global_store_dwordx2 v[96:97], v[76:77], off
	global_load_dwordx2 v[94:95], v[92:93], off
	global_load_dwordx2 v[96:97], v[20:21], off offset:2048
	global_load_dwordx4 v[76:79], v[26:27], off nt
	v_add_co_u32_e32 v98, vcc, s39, v18
	s_nop 1
	v_addc_co_u32_e32 v99, vcc, 0, v19, vcc
	global_load_dwordx2 v[100:101], v[98:99], off
	global_load_dwordx2 v[102:103], v[20:21], off offset:2560
	global_load_dwordx4 v[80:83], v[26:27], off offset:1024 nt
	v_add_co_u32_e32 v104, vcc, s40, v18
	s_nop 1
	v_addc_co_u32_e32 v105, vcc, 0, v19, vcc
	global_load_dwordx2 v[106:107], v[104:105], off
	global_load_dwordx2 v[108:109], v[20:21], off offset:3072
	global_load_dwordx4 v[84:87], v[26:27], off offset:2048 nt
	v_add_co_u32_e32 v110, vcc, s41, v18
	s_waitcnt vmcnt(7)
	v_lshlrev_b32_e32 v18, 16, v96
	v_addc_co_u32_e32 v111, vcc, 0, v19, vcc
	global_load_dwordx2 v[112:113], v[110:111], off
	global_load_dwordx2 v[114:115], v[20:21], off offset:3584
	global_load_dwordx4 v[88:91], v[26:27], off offset:3072 nt
	v_and_b32_e32 v19, 0xffff0000, v96
	v_lshlrev_b32_e32 v20, 16, v97
	v_and_b32_e32 v21, 0xffff0000, v97
	v_lshlrev_b32_e32 v26, 16, v94
	v_and_b32_e32 v27, 0xffff0000, v94
	v_lshlrev_b32_e32 v94, 16, v95
	v_and_b32_e32 v95, 0xffff0000, v95
	v_pk_mul_f32 v[96:97], v[16:17], v[18:19] op_sel_hi:[0,1]
	v_pk_mul_f32 v[18:19], v[16:17], v[20:21] op_sel_hi:[0,1]
	s_waitcnt vmcnt(9)
	v_pk_fma_f32 v[18:19], v[78:79], v[18:19], v[94:95]
	v_pk_fma_f32 v[20:21], v[76:77], v[96:97], v[26:27]
	s_waitcnt vmcnt(7)
	v_lshlrev_b32_e32 v76, 16, v103
	v_cvt_pk_bf16_f32 v26, v20, v21
	v_cvt_pk_bf16_f32 v27, v18, v19
	global_store_dwordx2 v[92:93], v[26:27], off
	v_lshlrev_b32_e32 v26, 16, v102
	v_and_b32_e32 v27, 0xffff0000, v102
	v_and_b32_e32 v77, 0xffff0000, v103
	v_lshlrev_b32_e32 v78, 16, v100
	v_and_b32_e32 v79, 0xffff0000, v100
	v_lshlrev_b32_e32 v92, 16, v101
	v_and_b32_e32 v93, 0xffff0000, v101
	v_pk_mul_f32 v[26:27], v[16:17], v[26:27] op_sel_hi:[0,1]
	v_pk_mul_f32 v[76:77], v[16:17], v[76:77] op_sel_hi:[0,1]
	s_waitcnt vmcnt(7)
	v_pk_fma_f32 v[76:77], v[82:83], v[76:77], v[92:93]
	v_pk_fma_f32 v[26:27], v[80:81], v[26:27], v[78:79]
	s_waitcnt vmcnt(5)
	v_lshlrev_b32_e32 v80, 16, v109
	v_cvt_pk_bf16_f32 v78, v26, v27
	v_cvt_pk_bf16_f32 v79, v76, v77
	global_store_dwordx2 v[98:99], v[78:79], off
	v_lshlrev_b32_e32 v78, 16, v108
	v_and_b32_e32 v79, 0xffff0000, v108
	v_and_b32_e32 v81, 0xffff0000, v109
	v_lshlrev_b32_e32 v82, 16, v106
	v_and_b32_e32 v83, 0xffff0000, v106
	v_lshlrev_b32_e32 v92, 16, v107
	v_and_b32_e32 v93, 0xffff0000, v107
	v_pk_mul_f32 v[78:79], v[16:17], v[78:79] op_sel_hi:[0,1]
	v_pk_mul_f32 v[80:81], v[16:17], v[80:81] op_sel_hi:[0,1]
	s_waitcnt vmcnt(5)
	v_pk_fma_f32 v[80:81], v[86:87], v[80:81], v[92:93]
	v_pk_fma_f32 v[78:79], v[84:85], v[78:79], v[82:83]
	v_cmp_eq_u32_e32 vcc, 0, v68
	v_cvt_pk_bf16_f32 v82, v78, v79
	v_cvt_pk_bf16_f32 v83, v80, v81
	global_store_dwordx2 v[104:105], v[82:83], off
	s_waitcnt vmcnt(5)
	v_lshlrev_b32_e32 v86, 16, v112
	s_waitcnt vmcnt(4)
	v_lshlrev_b32_e32 v82, 16, v114
	v_and_b32_e32 v83, 0xffff0000, v114
	v_lshlrev_b32_e32 v84, 16, v115
	v_and_b32_e32 v85, 0xffff0000, v115
	v_pk_mul_f32 v[82:83], v[16:17], v[82:83] op_sel_hi:[0,1]
	v_pk_mul_f32 v[84:85], v[16:17], v[84:85] op_sel_hi:[0,1]
	v_mul_f32_e32 v16, v23, v23
	v_fmac_f32_e32 v16, v22, v22
	v_add_f32_e32 v14, v14, v16
	v_add_f32_e32 v10, v14, v10
	v_add_f32_e32 v2, v10, v2
	v_add_f32_e32 v2, v2, v3
	v_mul_f32_e32 v3, v31, v31
	v_fmac_f32_e32 v3, v30, v30
	v_add_f32_e32 v3, v3, v4
	v_add_f32_e32 v2, v2, v3
	v_mul_f32_e32 v3, v35, v35
	v_mul_f32_e32 v4, v33, v33
	v_fmac_f32_e32 v3, v34, v34
	v_fmac_f32_e32 v4, v32, v32
	v_add_f32_e32 v3, v3, v4
	v_add_f32_e32 v2, v2, v3
	v_mul_f32_e32 v3, v39, v39
	v_mul_f32_e32 v4, v37, v37
	v_fmac_f32_e32 v3, v38, v38
	v_fmac_f32_e32 v4, v36, v36
	v_add_f32_e32 v3, v3, v4
	v_add_f32_e32 v2, v2, v3
	v_mul_f32_e32 v3, v43, v43
	v_mul_f32_e32 v4, v41, v41
	v_fmac_f32_e32 v3, v42, v42
	v_fmac_f32_e32 v4, v40, v40
	v_add_f32_e32 v3, v3, v4
	v_add_f32_e32 v2, v2, v3
	v_mul_f32_e32 v3, v47, v47
	v_mul_f32_e32 v4, v45, v45
	v_fmac_f32_e32 v3, v46, v46
	v_fmac_f32_e32 v4, v44, v44
	v_add_f32_e32 v3, v3, v4
	v_add_f32_e32 v2, v2, v3
	v_mul_f32_e32 v3, v51, v51
	v_mul_f32_e32 v4, v49, v49
	v_fmac_f32_e32 v3, v50, v50
	v_fmac_f32_e32 v4, v48, v48
	v_add_f32_e32 v3, v3, v4
	v_add_f32_e32 v2, v2, v3
	v_mul_f32_e32 v3, v55, v55
	v_mul_f32_e32 v4, v53, v53
	v_fmac_f32_e32 v3, v54, v54
	v_fmac_f32_e32 v4, v52, v52
	v_add_f32_e32 v3, v3, v4
	v_add_f32_e32 v2, v2, v3
	v_mul_f32_e32 v3, v59, v59
	v_mul_f32_e32 v4, v57, v57
	v_fmac_f32_e32 v3, v58, v58
	v_fmac_f32_e32 v4, v56, v56
	v_add_f32_e32 v3, v3, v4
	v_add_f32_e32 v2, v2, v3
	v_mul_f32_e32 v3, v21, v21
	v_mul_f32_e32 v4, v19, v19
	v_fmac_f32_e32 v3, v20, v20
	v_fmac_f32_e32 v4, v18, v18
	v_add_f32_e32 v3, v3, v4
	v_add_f32_e32 v2, v2, v3
	v_mul_f32_e32 v3, v27, v27
	v_mul_f32_e32 v4, v77, v77
	v_fmac_f32_e32 v3, v26, v26
	v_fmac_f32_e32 v4, v76, v76
	v_add_f32_e32 v3, v3, v4
	v_add_f32_e32 v2, v2, v3
	v_mul_f32_e32 v3, v79, v79
	v_mul_f32_e32 v4, v81, v81
	v_and_b32_e32 v87, 0xffff0000, v112
	v_lshlrev_b32_e32 v92, 16, v113
	v_and_b32_e32 v93, 0xffff0000, v113
	v_fmac_f32_e32 v3, v78, v78
	v_fmac_f32_e32 v4, v80, v80
	s_waitcnt vmcnt(3)
	v_pk_fma_f32 v[84:85], v[90:91], v[84:85], v[92:93]
	v_pk_fma_f32 v[82:83], v[88:89], v[82:83], v[86:87]
	v_add_f32_e32 v3, v3, v4
	v_add_f32_e32 v2, v2, v3
	v_mul_f32_e32 v3, v83, v83
	v_mul_f32_e32 v4, v85, v85
	v_fmac_f32_e32 v3, v82, v82
	v_fmac_f32_e32 v4, v84, v84
	v_add_f32_e32 v3, v3, v4
	v_add_f32_e32 v2, v2, v3
	ds_bpermute_b32 v3, v72, v2
	v_cvt_pk_bf16_f32 v86, v82, v83
	v_cvt_pk_bf16_f32 v87, v84, v85
	global_store_dwordx2 v[110:111], v[86:87], off
	s_waitcnt lgkmcnt(0)
	v_add_f32_e32 v2, v2, v3
	ds_bpermute_b32 v3, v73, v2
	s_waitcnt lgkmcnt(0)
	v_add_f32_e32 v2, v2, v3
	ds_bpermute_b32 v3, v74, v2
	s_waitcnt lgkmcnt(0)
	v_add_f32_e32 v2, v2, v3
	ds_bpermute_b32 v3, v71, v2
	s_waitcnt lgkmcnt(0)
	v_add_f32_e32 v2, v2, v3
	ds_bpermute_b32 v3, v70, v2
	s_waitcnt lgkmcnt(0)
	v_add_f32_e32 v2, v2, v3
	ds_bpermute_b32 v3, v69, v2
	s_and_saveexec_b64 s[4:5], vcc
	s_cbranch_execz .LBB0_579
	s_waitcnt lgkmcnt(0)
	v_add_f32_e32 v2, v2, v3
	v_fmamk_f32 v2, v2, 0x39800000, v67
	v_rsq_f32_e32 v2, v2
	s_add_u32 s44, s72, s0
	s_addc_u32 s45, s73, s1
	global_store_dword v15, v2, s[44:45]
	s_branch .LBB0_579

.LBB0_1296:
	s_mov_b32 s14, 9
	s_ashr_i32 s15, s14, 31
	s_lshl_b64 s[14:15], s[14:15], 3
	s_add_u32 s14, s68, s14
	s_addc_u32 s15, s69, s15
	s_waitcnt lgkmcnt(0)
	v_mov_b32_e32 v4, v0
	s_load_dwordx2 s[14:15], s[14:15], 0x0
	s_add_u32 s42, s70, s16
	v_and_b32_e32 v66, 63, v4
	v_lshlrev_b32_e32 v2, 2, v66
	s_addc_u32 s43, s71, s17
	global_load_dword v24, v2, s[42:43]
	s_add_u32 s42, s70, s4
	v_lshlrev_b32_e32 v2, 3, v66
	s_addc_u32 s43, s71, s5
	v_lshl_add_u64 v[8:9], s[42:43], 0, v[2:3]
	v_lshlrev_b32_e32 v2, 16, v4
	v_and_b32_e32 v4, 15, v4
	v_lshlrev_b32_e32 v4, 3, v4
	s_add_u32 s42, s70, s10
	v_and_or_b32 v4, v2, s18, v4
	v_mov_b32_e32 v5, v3
	s_addc_u32 s43, s71, s11
	v_add_co_u32_e32 v6, vcc, s30, v8
	v_lshl_add_u64 v[4:5], s[42:43], 0, v[4:5]
	s_nop 0
	v_addc_co_u32_e32 v7, vcc, 0, v9, vcc
	v_add_co_u32_e32 v34, vcc, s19, v4
	global_load_dwordx2 v[16:17], v[6:7], off offset:-4096
	s_nop 0
	v_addc_co_u32_e32 v35, vcc, 0, v5, vcc
	v_add_co_u32_e32 v36, vcc, s20, v8
	global_load_dwordx2 v[18:19], v[34:35], off
	s_nop 0
	v_addc_co_u32_e32 v37, vcc, 0, v9, vcc
	v_add_co_u32_e32 v38, vcc, s21, v4
	global_load_dwordx2 v[20:21], v[36:37], off offset:512
	s_nop 0
	v_addc_co_u32_e32 v39, vcc, 0, v5, vcc
	global_load_dwordx2 v[22:23], v[38:39], off
	global_load_dwordx2 v[40:41], v[36:37], off offset:1024
	v_add_co_u32_e32 v42, vcc, s22, v4
	v_lshlrev_b32_e32 v2, 4, v66
	s_nop 0
	v_addc_co_u32_e32 v43, vcc, 0, v5, vcc
	v_add_co_u32_e32 v46, vcc, s23, v4
	global_load_dwordx2 v[44:45], v[42:43], off
	s_nop 0
	v_addc_co_u32_e32 v47, vcc, 0, v5, vcc
	global_load_dwordx2 v[48:49], v[46:47], off
	global_load_dwordx2 v[50:51], v[36:37], off offset:1536
	s_waitcnt lgkmcnt(0)
	global_load_dwordx4 v[8:11], v2, s[14:15]
	global_load_dwordx4 v[12:15], v2, s[14:15] offset:1024
	global_load_dwordx4 v[26:29], v2, s[14:15] offset:2048
	global_load_dwordx4 v[30:33], v2, s[14:15] offset:3072
	s_waitcnt vmcnt(12)
	ds_bpermute_b32 v54, v1, v24
	s_waitcnt lgkmcnt(0)
	v_add_f32_e32 v24, v24, v54
	ds_bpermute_b32 v59, v201, v24
	s_waitcnt lgkmcnt(0)
	v_add_f32_e32 v24, v24, v59
	ds_bpermute_b32 v62, v205, v24
	s_waitcnt lgkmcnt(0)
	v_add_f32_e32 v24, v24, v62
	ds_bpermute_b32 v63, v211, v24
	s_waitcnt vmcnt(11)
	v_lshlrev_b32_e32 v52, 16, v16
	v_and_b32_e32 v53, 0xffff0000, v16
	v_lshlrev_b32_e32 v16, 16, v17
	v_and_b32_e32 v17, 0xffff0000, v17
	s_waitcnt lgkmcnt(0)
	v_add_f32_e32 v24, v24, v63
	ds_bpermute_b32 v65, v218, v24
	s_waitcnt vmcnt(10)
	v_lshlrev_b32_e32 v54, 16, v18
	v_and_b32_e32 v55, 0xffff0000, v18
	v_lshlrev_b32_e32 v18, 16, v19
	v_and_b32_e32 v19, 0xffff0000, v19
	s_waitcnt lgkmcnt(0)
	v_add_f32_e32 v24, v24, v65
	ds_bpermute_b32 v67, v219, v24
	s_waitcnt vmcnt(8)
	v_lshlrev_b32_e32 v58, 16, v22
	v_and_b32_e32 v59, 0xffff0000, v22
	v_lshlrev_b32_e32 v60, 16, v23
	v_and_b32_e32 v61, 0xffff0000, v23
	s_waitcnt lgkmcnt(0)
	v_add_f32_e32 v24, v24, v67
	v_fmamk_f32 v24, v24, 0x39800000, v25
	v_rsq_f32_e32 v24, v24
	s_waitcnt vmcnt(7)
	v_lshlrev_b32_e32 v22, 16, v40
	v_and_b32_e32 v23, 0xffff0000, v40
	v_lshlrev_b32_e32 v56, 16, v20
	v_pk_mul_f32 v[52:53], v[24:25], v[52:53] op_sel_hi:[0,1]
	v_pk_mul_f32 v[72:73], v[24:25], v[22:23] op_sel_hi:[0,1]
	s_waitcnt vmcnt(3)
	v_pk_fma_f32 v[22:23], v[8:9], v[52:53], v[54:55]
	v_add_co_u32_e32 v52, vcc, s24, v4
	v_and_b32_e32 v57, 0xffff0000, v20
	s_nop 0
	v_addc_co_u32_e32 v53, vcc, 0, v5, vcc
	v_lshlrev_b32_e32 v20, 16, v21
	v_and_b32_e32 v21, 0xffff0000, v21
	v_lshlrev_b32_e32 v62, 16, v44
	v_and_b32_e32 v63, 0xffff0000, v44
	v_pk_mul_f32 v[16:17], v[24:25], v[16:17] op_sel_hi:[0,1]
	v_pk_mul_f32 v[56:57], v[24:25], v[56:57] op_sel_hi:[0,1]
	v_add_co_u32_e32 v54, vcc, s26, v4
	v_lshlrev_b32_e32 v40, 16, v41
	v_and_b32_e32 v41, 0xffff0000, v41
	v_pk_mul_f32 v[70:71], v[24:25], v[20:21] op_sel_hi:[0,1]
	v_pk_fma_f32 v[20:21], v[10:11], v[16:17], v[18:19]
	s_waitcnt vmcnt(2)
	v_pk_fma_f32 v[18:19], v[12:13], v[56:57], v[58:59]
	s_waitcnt vmcnt(1)
	v_pk_fma_f32 v[12:13], v[26:27], v[72:73], v[62:63]
	v_cvt_pk_bf16_f32 v26, v22, v23
	v_cvt_pk_bf16_f32 v27, v20, v21
	v_addc_co_u32_e32 v55, vcc, 0, v5, vcc
	v_lshlrev_b32_e32 v44, 16, v45
	v_and_b32_e32 v45, 0xffff0000, v45
	v_lshlrev_b32_e32 v64, 16, v50
	v_and_b32_e32 v65, 0xffff0000, v50
	v_lshlrev_b32_e32 v50, 16, v51
	v_and_b32_e32 v51, 0xffff0000, v51
	v_pk_mul_f32 v[40:41], v[24:25], v[40:41] op_sel_hi:[0,1]
	v_pk_fma_f32 v[16:17], v[14:15], v[70:71], v[60:61]
	global_store_dwordx2 v[34:35], v[26:27], off
	v_cvt_pk_bf16_f32 v26, v18, v19
	v_cvt_pk_bf16_f32 v27, v16, v17
	v_add_co_u32_e32 v60, vcc, s27, v4
	v_lshlrev_b32_e32 v68, 16, v48
	v_and_b32_e32 v69, 0xffff0000, v48
	v_lshlrev_b32_e32 v48, 16, v49
	v_and_b32_e32 v49, 0xffff0000, v49
	v_pk_mul_f32 v[64:65], v[24:25], v[64:65] op_sel_hi:[0,1]
	v_pk_mul_f32 v[50:51], v[24:25], v[50:51] op_sel_hi:[0,1]
	v_pk_fma_f32 v[10:11], v[28:29], v[40:41], v[44:45]
	global_store_dwordx2 v[38:39], v[26:27], off
	v_cvt_pk_bf16_f32 v26, v12, v13
	v_cvt_pk_bf16_f32 v27, v10, v11
	v_addc_co_u32_e32 v61, vcc, 0, v5, vcc
	s_waitcnt vmcnt(2)
	v_pk_fma_f32 v[8:9], v[32:33], v[50:51], v[48:49]
	v_pk_fma_f32 v[14:15], v[30:31], v[64:65], v[68:69]
	global_store_dwordx2 v[42:43], v[26:27], off
	v_cvt_pk_bf16_f32 v26, v14, v15
	v_cvt_pk_bf16_f32 v27, v8, v9
	global_store_dwordx2 v[46:47], v[26:27], off
	v_add_co_u32_e32 v64, vcc, s28, v4
	v_lshl_add_u64 v[42:43], s[14:15], 0, v[2:3]
	s_nop 0
	v_addc_co_u32_e32 v65, vcc, 0, v5, vcc
	global_load_dwordx2 v[30:31], v[36:37], off offset:2048
	global_load_dwordx2 v[32:33], v[52:53], off
	global_load_dwordx2 v[34:35], v[36:37], off offset:2560
	v_add_co_u32_e32 v70, vcc, s31, v42
	global_load_dwordx2 v[56:57], v[54:55], off
	global_load_dwordx2 v[58:59], v[36:37], off offset:3072
	global_load_dwordx2 v[62:63], v[60:61], off
	global_load_dwordx2 v[68:69], v[64:65], off
	v_addc_co_u32_e32 v71, vcc, 0, v43, vcc
	global_load_dwordx2 v[36:37], v[36:37], off offset:3584
	v_add_co_u32_e32 v48, vcc, s25, v42
	global_load_dwordx4 v[26:29], v[70:71], off offset:-4096 nt
	s_nop 0
	v_addc_co_u32_e32 v49, vcc, 0, v43, vcc
	global_load_dwordx4 v[38:41], v[48:49], off offset:1024 nt
	global_load_dwordx4 v[44:47], v[48:49], off offset:2048 nt
	s_nop 0
	global_load_dwordx4 v[48:51], v[48:49], off offset:3072 nt
	v_mul_f32_e32 v2, v23, v23
	v_mul_f32_e32 v21, v21, v21
	v_mul_f32_e32 v19, v19, v19
	v_mul_f32_e32 v17, v17, v17
	v_fmac_f32_e32 v2, v22, v22
	v_fmac_f32_e32 v21, v20, v20
	v_fmac_f32_e32 v19, v18, v18
	v_fmac_f32_e32 v17, v16, v16
	v_mul_f32_e32 v13, v13, v13
	v_mul_f32_e32 v11, v11, v11
	v_add_f32_e32 v2, v2, v21
	v_add_f32_e32 v16, v19, v17
	v_fmac_f32_e32 v13, v12, v12
	v_fmac_f32_e32 v11, v10, v10
	v_add_f32_e32 v2, v2, v16
	v_add_f32_e32 v10, v13, v11
	v_add_f32_e32 v2, v2, v10
	v_mul_f32_e32 v10, v15, v15
	v_mul_f32_e32 v9, v9, v9
	v_fmac_f32_e32 v10, v14, v14
	v_fmac_f32_e32 v9, v8, v8
	v_add_f32_e32 v8, v10, v9
	v_add_f32_e32 v2, v2, v8
	s_waitcnt vmcnt(11)
	v_lshlrev_b32_e32 v72, 16, v30
	v_and_b32_e32 v73, 0xffff0000, v30
	v_lshlrev_b32_e32 v30, 16, v31
	v_and_b32_e32 v31, 0xffff0000, v31
	s_waitcnt vmcnt(9)
	v_lshlrev_b32_e32 v76, 16, v34
	v_and_b32_e32 v77, 0xffff0000, v34
	v_lshlrev_b32_e32 v74, 16, v32
	v_and_b32_e32 v75, 0xffff0000, v32
	v_lshlrev_b32_e32 v32, 16, v33
	v_and_b32_e32 v33, 0xffff0000, v33
	v_lshlrev_b32_e32 v34, 16, v35
	v_and_b32_e32 v35, 0xffff0000, v35
	s_waitcnt vmcnt(8)
	v_lshlrev_b32_e32 v78, 16, v56
	v_and_b32_e32 v79, 0xffff0000, v56
	s_waitcnt vmcnt(4)
	v_lshlrev_b32_e32 v84, 16, v36
	v_and_b32_e32 v85, 0xffff0000, v36
	v_lshlrev_b32_e32 v86, 16, v37
	v_and_b32_e32 v87, 0xffff0000, v37
	v_pk_mul_f32 v[36:37], v[24:25], v[72:73] op_sel_hi:[0,1]
	v_pk_mul_f32 v[30:31], v[24:25], v[30:31] op_sel_hi:[0,1]
	v_pk_mul_f32 v[72:73], v[24:25], v[76:77] op_sel_hi:[0,1]
	v_lshlrev_b32_e32 v56, 16, v57
	v_and_b32_e32 v57, 0xffff0000, v57
	v_lshlrev_b32_e32 v80, 16, v58
	v_and_b32_e32 v81, 0xffff0000, v58
	v_lshlrev_b32_e32 v58, 16, v59
	v_and_b32_e32 v59, 0xffff0000, v59
	v_pk_mul_f32 v[76:77], v[24:25], v[34:35] op_sel_hi:[0,1]
	s_waitcnt vmcnt(3)
	v_pk_fma_f32 v[34:35], v[28:29], v[30:31], v[32:33]
	v_pk_fma_f32 v[36:37], v[26:27], v[36:37], v[74:75]
	s_waitcnt vmcnt(2)
	v_pk_fma_f32 v[32:33], v[38:39], v[72:73], v[78:79]
	v_cvt_pk_bf16_f32 v38, v36, v37
	v_cvt_pk_bf16_f32 v39, v34, v35
	v_lshlrev_b32_e32 v82, 16, v62
	v_and_b32_e32 v83, 0xffff0000, v62
	v_lshlrev_b32_e32 v62, 16, v63
	v_and_b32_e32 v63, 0xffff0000, v63
	v_pk_mul_f32 v[80:81], v[24:25], v[80:81] op_sel_hi:[0,1]
	v_pk_mul_f32 v[58:59], v[24:25], v[58:59] op_sel_hi:[0,1]
	v_pk_fma_f32 v[30:31], v[40:41], v[76:77], v[56:57]
	global_store_dwordx2 v[52:53], v[38:39], off
	v_cvt_pk_bf16_f32 v38, v32, v33
	v_cvt_pk_bf16_f32 v39, v30, v31
	s_waitcnt vmcnt(2)
	v_pk_fma_f32 v[26:27], v[46:47], v[58:59], v[62:63]
	v_pk_fma_f32 v[28:29], v[44:45], v[80:81], v[82:83]
	global_store_dwordx2 v[54:55], v[38:39], off
	v_cvt_pk_bf16_f32 v38, v28, v29
	v_cvt_pk_bf16_f32 v39, v26, v27
	v_lshlrev_b32_e32 v88, 16, v68
	global_store_dwordx2 v[60:61], v[38:39], off
	v_and_b32_e32 v89, 0xffff0000, v68
	v_lshlrev_b32_e32 v38, 16, v69
	v_and_b32_e32 v39, 0xffff0000, v69
	v_pk_mul_f32 v[40:41], v[24:25], v[84:85] op_sel_hi:[0,1]
	v_pk_mul_f32 v[44:45], v[24:25], v[86:87] op_sel_hi:[0,1]
	v_add_co_u32_e32 v54, vcc, s29, v4
	s_waitcnt vmcnt(3)
	v_pk_fma_f32 v[38:39], v[50:51], v[44:45], v[38:39]
	v_pk_fma_f32 v[40:41], v[48:49], v[40:41], v[88:89]
	v_addc_co_u32_e32 v55, vcc, 0, v5, vcc
	v_cvt_pk_bf16_f32 v44, v40, v41
	v_cvt_pk_bf16_f32 v45, v38, v39
	global_store_dwordx2 v[64:65], v[44:45], off
	v_add_co_u32_e32 v72, vcc, s33, v4
	global_load_dwordx2 v[52:53], v[6:7], off
	s_nop 0
	v_addc_co_u32_e32 v73, vcc, 0, v5, vcc
	global_load_dwordx2 v[56:57], v[54:55], off
	global_load_dwordx2 v[58:59], v[6:7], off offset:512
	global_load_dwordx2 v[60:61], v[72:73], off
	global_load_dwordx2 v[74:75], v[6:7], off offset:1024
	v_add_co_u32_e32 v76, vcc, s34, v4
	v_mul_f32_e32 v8, v37, v37
	s_nop 0
	v_addc_co_u32_e32 v77, vcc, 0, v5, vcc
	v_add_co_u32_e32 v82, vcc, s35, v4
	global_load_dwordx2 v[78:79], v[76:77], off
	global_load_dwordx2 v[80:81], v[6:7], off offset:1536
	v_addc_co_u32_e32 v83, vcc, 0, v5, vcc
	global_load_dwordx2 v[84:85], v[82:83], off
	global_load_dwordx4 v[44:47], v[70:71], off nt
	global_load_dwordx4 v[48:51], v[70:71], off offset:1024 nt
	global_load_dwordx4 v[62:65], v[70:71], off offset:2048 nt
	s_nop 0
	global_load_dwordx4 v[68:71], v[70:71], off offset:3072 nt
	v_mul_f32_e32 v9, v35, v35
	v_fmac_f32_e32 v8, v36, v36
	v_fmac_f32_e32 v9, v34, v34
	v_add_f32_e32 v8, v8, v9
	v_add_f32_e32 v2, v2, v8
	v_mul_f32_e32 v8, v33, v33
	v_mul_f32_e32 v9, v31, v31
	v_fmac_f32_e32 v8, v32, v32
	v_fmac_f32_e32 v9, v30, v30
	v_add_f32_e32 v8, v8, v9
	v_add_f32_e32 v2, v2, v8
	v_mul_f32_e32 v8, v29, v29
	v_mul_f32_e32 v9, v27, v27
	v_fmac_f32_e32 v8, v28, v28
	v_fmac_f32_e32 v9, v26, v26
	v_add_f32_e32 v8, v8, v9
	v_add_f32_e32 v2, v2, v8
	v_mul_f32_e32 v8, v41, v41
	v_mul_f32_e32 v9, v39, v39
	v_fmac_f32_e32 v8, v40, v40
	v_fmac_f32_e32 v9, v38, v38
	v_add_f32_e32 v8, v8, v9
	v_add_f32_e32 v2, v2, v8
	s_waitcnt vmcnt(11)
	v_lshlrev_b32_e32 v86, 16, v52
	v_and_b32_e32 v87, 0xffff0000, v52
	v_lshlrev_b32_e32 v52, 16, v53
	v_and_b32_e32 v53, 0xffff0000, v53
	s_waitcnt vmcnt(10)
	v_lshlrev_b32_e32 v88, 16, v56
	v_and_b32_e32 v89, 0xffff0000, v56
	v_lshlrev_b32_e32 v56, 16, v57
	v_and_b32_e32 v57, 0xffff0000, v57
	s_waitcnt vmcnt(9)
	v_lshlrev_b32_e32 v90, 16, v58
	v_and_b32_e32 v91, 0xffff0000, v58
	v_lshlrev_b32_e32 v58, 16, v59
	v_and_b32_e32 v59, 0xffff0000, v59
	s_waitcnt vmcnt(8)
	v_lshlrev_b32_e32 v92, 16, v60
	v_and_b32_e32 v93, 0xffff0000, v60
	v_lshlrev_b32_e32 v94, 16, v61
	v_and_b32_e32 v95, 0xffff0000, v61
	s_waitcnt vmcnt(7)
	v_lshlrev_b32_e32 v60, 16, v74
	v_and_b32_e32 v61, 0xffff0000, v74
	v_pk_mul_f32 v[86:87], v[24:25], v[86:87] op_sel_hi:[0,1]
	v_pk_mul_f32 v[52:53], v[24:25], v[52:53] op_sel_hi:[0,1]
	v_lshlrev_b32_e32 v74, 16, v75
	v_and_b32_e32 v75, 0xffff0000, v75
	v_pk_mul_f32 v[90:91], v[24:25], v[90:91] op_sel_hi:[0,1]
	v_pk_mul_f32 v[102:103], v[24:25], v[58:59] op_sel_hi:[0,1]
	v_pk_mul_f32 v[104:105], v[24:25], v[60:61] op_sel_hi:[0,1]
	s_waitcnt vmcnt(3)
	v_pk_fma_f32 v[58:59], v[46:47], v[52:53], v[56:57]
	v_pk_fma_f32 v[60:61], v[44:45], v[86:87], v[88:89]
	v_lshlrev_b32_e32 v96, 16, v78
	v_cvt_pk_bf16_f32 v44, v60, v61
	v_cvt_pk_bf16_f32 v45, v58, v59
	v_and_b32_e32 v97, 0xffff0000, v78
	v_lshlrev_b32_e32 v78, 16, v79
	v_and_b32_e32 v79, 0xffff0000, v79
	v_pk_mul_f32 v[74:75], v[24:25], v[74:75] op_sel_hi:[0,1]
	s_waitcnt vmcnt(2)
	v_pk_fma_f32 v[52:53], v[50:51], v[102:103], v[94:95]
	v_pk_fma_f32 v[56:57], v[48:49], v[90:91], v[92:93]
	global_store_dwordx2 v[54:55], v[44:45], off
	v_cvt_pk_bf16_f32 v44, v56, v57
	v_cvt_pk_bf16_f32 v45, v52, v53
	v_lshlrev_b32_e32 v98, 16, v80
	v_and_b32_e32 v99, 0xffff0000, v80
	v_lshlrev_b32_e32 v80, 16, v81
	v_and_b32_e32 v81, 0xffff0000, v81
	s_waitcnt vmcnt(2)
	v_pk_fma_f32 v[46:47], v[64:65], v[74:75], v[78:79]
	v_pk_fma_f32 v[50:51], v[62:63], v[104:105], v[96:97]
	global_store_dwordx2 v[72:73], v[44:45], off
	v_cvt_pk_bf16_f32 v44, v50, v51
	v_cvt_pk_bf16_f32 v45, v46, v47
	v_lshlrev_b32_e32 v100, 16, v84
	global_store_dwordx2 v[76:77], v[44:45], off
	v_and_b32_e32 v101, 0xffff0000, v84
	v_lshlrev_b32_e32 v44, 16, v85
	v_and_b32_e32 v45, 0xffff0000, v85
	v_pk_mul_f32 v[48:49], v[24:25], v[98:99] op_sel_hi:[0,1]
	v_pk_mul_f32 v[54:55], v[24:25], v[80:81] op_sel_hi:[0,1]
	s_waitcnt vmcnt(3)
	v_pk_fma_f32 v[62:63], v[70:71], v[54:55], v[44:45]
	v_pk_fma_f32 v[64:65], v[68:69], v[48:49], v[100:101]
	v_mul_f32_e32 v8, v61, v61
	v_cvt_pk_bf16_f32 v44, v64, v65
	v_cvt_pk_bf16_f32 v45, v62, v63
	global_store_dwordx2 v[82:83], v[44:45], off
	v_add_co_u32_e32 v44, vcc, s36, v4
	global_load_dwordx2 v[84:85], v[6:7], off offset:2048
	s_nop 0
	v_addc_co_u32_e32 v45, vcc, 0, v5, vcc
	v_add_co_u32_e32 v48, vcc, s38, v4
	global_load_dwordx2 v[86:87], v[44:45], off
	global_load_dwordx2 v[88:89], v[6:7], off offset:2560
	v_addc_co_u32_e32 v49, vcc, 0, v5, vcc
	v_add_co_u32_e32 v54, vcc, s39, v4
	global_load_dwordx2 v[90:91], v[48:49], off
	global_load_dwordx2 v[92:93], v[6:7], off offset:3072
	v_addc_co_u32_e32 v55, vcc, 0, v5, vcc
	v_add_co_u32_e32 v4, vcc, s40, v4
	global_load_dwordx2 v[94:95], v[54:55], off
	s_nop 0
	global_load_dwordx2 v[6:7], v[6:7], off offset:3584
	v_addc_co_u32_e32 v5, vcc, 0, v5, vcc
	v_add_co_u32_e32 v42, vcc, s37, v42
	global_load_dwordx2 v[96:97], v[4:5], off
	s_nop 0
	v_addc_co_u32_e32 v43, vcc, 0, v43, vcc
	global_load_dwordx4 v[68:71], v[42:43], off nt
	global_load_dwordx4 v[72:75], v[42:43], off offset:1024 nt
	global_load_dwordx4 v[76:79], v[42:43], off offset:2048 nt
	global_load_dwordx4 v[80:83], v[42:43], off offset:3072 nt
	v_mul_f32_e32 v9, v59, v59
	v_fmac_f32_e32 v8, v60, v60
	v_fmac_f32_e32 v9, v58, v58
	v_add_f32_e32 v8, v8, v9
	v_add_f32_e32 v2, v2, v8
	v_mul_f32_e32 v8, v57, v57
	v_mul_f32_e32 v9, v53, v53
	v_fmac_f32_e32 v8, v56, v56
	v_fmac_f32_e32 v9, v52, v52
	v_add_f32_e32 v8, v8, v9
	v_add_f32_e32 v2, v2, v8
	v_mul_f32_e32 v8, v51, v51
	v_mul_f32_e32 v9, v47, v47
	v_fmac_f32_e32 v8, v50, v50
	v_fmac_f32_e32 v9, v46, v46
	v_add_f32_e32 v8, v8, v9
	v_add_f32_e32 v2, v2, v8
	v_mul_f32_e32 v8, v65, v65
	v_mul_f32_e32 v9, v63, v63
	v_fmac_f32_e32 v8, v64, v64
	v_fmac_f32_e32 v9, v62, v62
	v_add_f32_e32 v8, v8, v9
	v_add_f32_e32 v2, v2, v8
	v_cmp_eq_u32_e32 vcc, 0, v66
	s_waitcnt vmcnt(11)
	v_lshlrev_b32_e32 v42, 16, v84
	v_and_b32_e32 v43, 0xffff0000, v84
	v_lshlrev_b32_e32 v84, 16, v85
	v_and_b32_e32 v85, 0xffff0000, v85
	s_waitcnt vmcnt(10)
	v_lshlrev_b32_e32 v98, 16, v86
	v_and_b32_e32 v99, 0xffff0000, v86
	v_lshlrev_b32_e32 v86, 16, v87
	v_and_b32_e32 v87, 0xffff0000, v87
	v_pk_mul_f32 v[42:43], v[24:25], v[42:43] op_sel_hi:[0,1]
	v_pk_mul_f32 v[84:85], v[24:25], v[84:85] op_sel_hi:[0,1]
	s_waitcnt vmcnt(9)
	v_lshlrev_b32_e32 v100, 16, v88
	v_and_b32_e32 v101, 0xffff0000, v88
	v_lshlrev_b32_e32 v88, 16, v89
	v_and_b32_e32 v89, 0xffff0000, v89
	s_waitcnt vmcnt(8)
	v_lshlrev_b32_e32 v102, 16, v90
	v_and_b32_e32 v103, 0xffff0000, v90
	v_lshlrev_b32_e32 v90, 16, v91
	v_and_b32_e32 v91, 0xffff0000, v91
	v_pk_mul_f32 v[100:101], v[24:25], v[100:101] op_sel_hi:[0,1]
	v_pk_mul_f32 v[88:89], v[24:25], v[88:89] op_sel_hi:[0,1]
	s_waitcnt vmcnt(3)
	v_pk_fma_f32 v[70:71], v[70:71], v[84:85], v[86:87]
	v_pk_fma_f32 v[42:43], v[68:69], v[42:43], v[98:99]
	v_mul_f32_e32 v9, v71, v71
	v_mul_f32_e32 v8, v43, v43
	v_fmac_f32_e32 v8, v42, v42
	v_fmac_f32_e32 v9, v70, v70
	s_waitcnt vmcnt(2)
	v_pk_fma_f32 v[68:69], v[74:75], v[88:89], v[90:91]
	v_pk_fma_f32 v[72:73], v[72:73], v[100:101], v[102:103]
	v_add_f32_e32 v8, v8, v9
	v_lshlrev_b32_e32 v104, 16, v92
	v_and_b32_e32 v105, 0xffff0000, v92
	v_lshlrev_b32_e32 v92, 16, v93
	v_and_b32_e32 v93, 0xffff0000, v93
	v_add_f32_e32 v2, v2, v8
	v_mul_f32_e32 v8, v73, v73
	v_mul_f32_e32 v9, v69, v69
	v_lshlrev_b32_e32 v106, 16, v94
	v_and_b32_e32 v107, 0xffff0000, v94
	v_lshlrev_b32_e32 v94, 16, v95
	v_and_b32_e32 v95, 0xffff0000, v95
	v_pk_mul_f32 v[104:105], v[24:25], v[104:105] op_sel_hi:[0,1]
	v_pk_mul_f32 v[92:93], v[24:25], v[92:93] op_sel_hi:[0,1]
	v_fmac_f32_e32 v8, v72, v72
	v_fmac_f32_e32 v9, v68, v68
	s_waitcnt vmcnt(1)
	v_pk_fma_f32 v[74:75], v[78:79], v[92:93], v[94:95]
	v_pk_fma_f32 v[76:77], v[76:77], v[104:105], v[106:107]
	v_add_f32_e32 v8, v8, v9
	v_lshlrev_b32_e32 v108, 16, v6
	v_and_b32_e32 v109, 0xffff0000, v6
	v_lshlrev_b32_e32 v6, 16, v7
	v_and_b32_e32 v7, 0xffff0000, v7
	v_add_f32_e32 v2, v2, v8
	v_mul_f32_e32 v8, v77, v77
	v_mul_f32_e32 v9, v75, v75
	v_lshlrev_b32_e32 v110, 16, v96
	v_and_b32_e32 v111, 0xffff0000, v96
	v_lshlrev_b32_e32 v78, 16, v97
	v_and_b32_e32 v79, 0xffff0000, v97
	v_pk_mul_f32 v[84:85], v[24:25], v[108:109] op_sel_hi:[0,1]
	v_pk_mul_f32 v[6:7], v[24:25], v[6:7] op_sel_hi:[0,1]
	v_fmac_f32_e32 v8, v76, v76
	v_fmac_f32_e32 v9, v74, v74
	s_waitcnt vmcnt(0)
	v_pk_fma_f32 v[6:7], v[82:83], v[6:7], v[78:79]
	v_pk_fma_f32 v[78:79], v[80:81], v[84:85], v[110:111]
	v_add_f32_e32 v8, v8, v9
	v_add_f32_e32 v2, v2, v8
	v_mul_f32_e32 v8, v79, v79
	v_mul_f32_e32 v9, v7, v7
	v_fmac_f32_e32 v8, v78, v78
	v_fmac_f32_e32 v9, v6, v6
	v_add_f32_e32 v8, v8, v9
	v_add_f32_e32 v2, v2, v8
	ds_bpermute_b32 v8, v1, v2
	s_waitcnt lgkmcnt(0)
	v_add_f32_e32 v2, v2, v8
	ds_bpermute_b32 v8, v201, v2
	s_waitcnt lgkmcnt(0)
	v_add_f32_e32 v2, v2, v8
	ds_bpermute_b32 v10, v205, v2
	v_cvt_pk_bf16_f32 v8, v42, v43
	v_cvt_pk_bf16_f32 v9, v70, v71
	global_store_dwordx2 v[44:45], v[8:9], off
	v_cvt_pk_bf16_f32 v8, v72, v73
	s_waitcnt lgkmcnt(0)
	v_add_f32_e32 v2, v2, v10
	ds_bpermute_b32 v10, v211, v2
	v_cvt_pk_bf16_f32 v9, v68, v69
	global_store_dwordx2 v[48:49], v[8:9], off
	v_cvt_pk_bf16_f32 v8, v76, v77
	v_cvt_pk_bf16_f32 v9, v74, v75
	s_waitcnt lgkmcnt(0)
	v_add_f32_e32 v2, v2, v10
	ds_bpermute_b32 v10, v218, v2
	global_store_dwordx2 v[54:55], v[8:9], off
	v_cvt_pk_bf16_f32 v8, v78, v79
	v_cvt_pk_bf16_f32 v9, v6, v7
	global_store_dwordx2 v[4:5], v[8:9], off
	s_waitcnt lgkmcnt(0)
	v_add_f32_e32 v2, v2, v10
	ds_bpermute_b32 v4, v219, v2
	s_and_saveexec_b64 s[14:15], vcc
	s_cbranch_execz .LBB0_1295
	s_waitcnt lgkmcnt(0)
	v_add_f32_e32 v2, v2, v4
	v_fmamk_f32 v2, v2, 0x39800000, v25
	v_rsq_f32_e32 v2, v2
	s_add_u32 s42, s70, s0
	s_addc_u32 s43, s71, s1
	global_store_dword v3, v2, s[42:43]
	s_branch .LBB0_1295

.LBB0_2262:
	s_mov_b32 s2, 19
	s_ashr_i32 s3, s2, 31
	s_lshl_b64 s[2:3], s[2:3], 3
	s_add_u32 s2, s68, s2
	s_addc_u32 s3, s69, s3
	s_load_dwordx2 s[4:5], s[2:3], 0x0
	s_mov_b32 s2, 24
	s_ashr_i32 s3, s2, 31
	s_lshl_b64 s[2:3], s[2:3], 3
	s_add_u32 s2, s68, s2
	s_addc_u32 s3, s69, s3
	v_mov_b32_e32 v6, v0
	s_load_dwordx2 s[2:3], s[2:3], 0x0
	s_add_u32 s16, s70, s0
	v_and_b32_e32 v4, 63, v6
	v_lshlrev_b32_e32 v2, 2, v4
	s_addc_u32 s17, s71, s1
	global_load_dword v2, v2, s[16:17]
	s_add_u32 s16, s70, s10
	v_lshlrev_b32_e32 v84, 15, v6
	v_lshlrev_b32_e32 v14, 3, v4
	s_addc_u32 s17, s71, s11
	v_lshlrev_b32_e32 v7, 16, v6
	v_lshl_add_u64 v[8:9], s[16:17], 0, v[14:15]
	s_mov_b32 s16, 0x300000
	s_mov_b32 s50, 0x36500000
	v_lshlrev_b32_e32 v14, 4, v4
	s_waitcnt lgkmcnt(0)
	v_lshl_add_u64 v[4:5], s[4:5], 0, v[14:15]
	s_waitcnt vmcnt(0)
	ds_bpermute_b32 v3, v1, v2
	s_waitcnt lgkmcnt(0)
	v_add_f32_e32 v2, v2, v3
	ds_bpermute_b32 v3, v201, v2
	s_waitcnt lgkmcnt(0)
	v_add_f32_e32 v2, v2, v3
	ds_bpermute_b32 v3, v205, v2
	s_waitcnt lgkmcnt(0)
	v_add_f32_e32 v2, v2, v3
	ds_bpermute_b32 v3, v211, v2
	s_waitcnt lgkmcnt(0)
	v_add_f32_e32 v2, v2, v3
	ds_bpermute_b32 v3, v218, v2
	s_waitcnt lgkmcnt(0)
	v_add_f32_e32 v2, v2, v3
	ds_bpermute_b32 v3, v219, v2
	s_waitcnt lgkmcnt(0)
	v_add_f32_e32 v2, v2, v3
	v_lshlrev_b32_e32 v3, 2, v6
	v_and_b32_e32 v6, 15, v6
	v_lshlrev_b32_e32 v6, 3, v6
	v_and_or_b32 v6, v7, s16, v6
	s_add_u32 s16, s70, s6
	v_mov_b32_e32 v7, v15
	s_addc_u32 s17, s71, s7
	v_lshl_add_u64 v[6:7], s[16:17], 0, v[6:7]
	v_add_co_u32_e32 v28, vcc, s50, v6
	s_mov_b32 s50, 0x3e500000
	s_nop 0
	v_addc_co_u32_e32 v29, vcc, 0, v7, vcc
	v_add_co_u32_e32 v34, vcc, s50, v8
	global_load_dwordx2 v[30:31], v[28:29], off
	s_nop 0
	v_addc_co_u32_e32 v35, vcc, 0, v9, vcc
	v_add_co_u32_e32 v8, vcc, s21, v8
	s_mov_b32 s50, 0x36900000
	s_nop 0
	v_addc_co_u32_e32 v9, vcc, 0, v9, vcc
	global_load_dwordx2 v[36:37], v[8:9], off offset:-4096
	global_load_dwordx4 v[10:13], v14, s[4:5]
	v_add_co_u32_e32 v38, vcc, s50, v6
	s_mov_b32 s50, 0x36d00000
	s_nop 0
	v_addc_co_u32_e32 v39, vcc, 0, v7, vcc
	global_load_dwordx2 v[40:41], v[38:39], off
	global_load_dwordx2 v[42:43], v[34:35], off offset:512
	global_load_dwordx4 v[16:19], v14, s[4:5] offset:1024
	v_add_co_u32_e32 v44, vcc, s50, v6
	s_mov_b32 s50, 0x37100000
	s_nop 0
	v_addc_co_u32_e32 v45, vcc, 0, v7, vcc
	global_load_dwordx2 v[46:47], v[44:45], off
	global_load_dwordx2 v[48:49], v[34:35], off offset:1024
	global_load_dwordx4 v[20:23], v14, s[4:5] offset:2048
	v_add_co_u32_e32 v50, vcc, s50, v6
	v_fmamk_f32 v2, v2, 0x39800000, v33
	s_nop 0
	v_addc_co_u32_e32 v51, vcc, 0, v7, vcc
	global_load_dwordx2 v[52:53], v[50:51], off
	global_load_dwordx2 v[54:55], v[34:35], off offset:1536
	global_load_dwordx4 v[24:27], v14, s[4:5] offset:3072
	v_rsq_f32_e32 v2, v2
	s_mov_b32 s4, 0x37500000
	v_and_b32_e32 v85, 0x7c, v3
	s_add_i32 s49, s49, s74
	s_add_u32 s6, s6, s8
	s_addc_u32 s7, s7, s9
	s_add_u32 s10, s10, s12
	s_addc_u32 s11, s11, s13
	s_add_u32 s0, s0, s14
	s_addc_u32 s1, s1, s15
	s_cmpk_gt_i32 s49, 0x1fff
	s_waitcnt vmcnt(11)
	v_lshlrev_b32_e32 v58, 16, v30
	v_and_b32_e32 v59, 0xffff0000, v30
	v_lshlrev_b32_e32 v30, 16, v31
	v_and_b32_e32 v31, 0xffff0000, v31
	s_waitcnt vmcnt(10)
	v_lshlrev_b32_e32 v56, 16, v36
	v_and_b32_e32 v57, 0xffff0000, v36
	v_lshlrev_b32_e32 v36, 16, v37
	v_and_b32_e32 v37, 0xffff0000, v37
	v_pk_mul_f32 v[56:57], v[2:3], v[56:57] op_sel_hi:[0,1]
	v_pk_mul_f32 v[36:37], v[2:3], v[36:37] op_sel_hi:[0,1]
	s_waitcnt vmcnt(9)
	v_pk_fma_f32 v[68:69], v[12:13], v[36:37], v[30:31]
	v_pk_fma_f32 v[82:83], v[10:11], v[56:57], v[58:59]
	s_waitcnt vmcnt(7)
	v_lshlrev_b32_e32 v12, 16, v43
	v_cvt_pk_bf16_f32 v10, v82, v83
	v_cvt_pk_bf16_f32 v11, v68, v69
	global_store_dwordx2 v[28:29], v[10:11], off
	v_lshlrev_b32_e32 v10, 16, v42
	v_and_b32_e32 v11, 0xffff0000, v42
	v_and_b32_e32 v13, 0xffff0000, v43
	v_lshlrev_b32_e32 v28, 16, v40
	v_and_b32_e32 v29, 0xffff0000, v40
	v_lshlrev_b32_e32 v30, 16, v41
	v_and_b32_e32 v31, 0xffff0000, v41
	v_pk_mul_f32 v[10:11], v[2:3], v[10:11] op_sel_hi:[0,1]
	v_pk_mul_f32 v[12:13], v[2:3], v[12:13] op_sel_hi:[0,1]
	s_waitcnt vmcnt(7)
	v_pk_fma_f32 v[78:79], v[18:19], v[12:13], v[30:31]
	v_pk_fma_f32 v[80:81], v[16:17], v[10:11], v[28:29]
	s_waitcnt vmcnt(5)
	v_lshlrev_b32_e32 v12, 16, v49
	v_cvt_pk_bf16_f32 v10, v80, v81
	v_cvt_pk_bf16_f32 v11, v78, v79
	global_store_dwordx2 v[38:39], v[10:11], off
	v_lshlrev_b32_e32 v10, 16, v48
	v_and_b32_e32 v11, 0xffff0000, v48
	v_and_b32_e32 v13, 0xffff0000, v49
	v_lshlrev_b32_e32 v16, 16, v46
	v_and_b32_e32 v17, 0xffff0000, v46
	v_lshlrev_b32_e32 v18, 16, v47
	v_and_b32_e32 v19, 0xffff0000, v47
	v_pk_mul_f32 v[10:11], v[2:3], v[10:11] op_sel_hi:[0,1]
	v_pk_mul_f32 v[12:13], v[2:3], v[12:13] op_sel_hi:[0,1]
	s_waitcnt vmcnt(5)
	v_pk_fma_f32 v[74:75], v[22:23], v[12:13], v[18:19]
	v_pk_fma_f32 v[76:77], v[20:21], v[10:11], v[16:17]
	s_waitcnt vmcnt(3)
	v_lshlrev_b32_e32 v12, 16, v55
	v_cvt_pk_bf16_f32 v10, v76, v77
	v_cvt_pk_bf16_f32 v11, v74, v75
	global_store_dwordx2 v[44:45], v[10:11], off
	v_lshlrev_b32_e32 v10, 16, v54
	v_and_b32_e32 v11, 0xffff0000, v54
	v_and_b32_e32 v13, 0xffff0000, v55
	v_add_co_u32_e32 v28, vcc, s4, v6
	v_lshlrev_b32_e32 v16, 16, v52
	v_and_b32_e32 v17, 0xffff0000, v52
	v_lshlrev_b32_e32 v18, 16, v53
	v_and_b32_e32 v19, 0xffff0000, v53
	v_pk_mul_f32 v[10:11], v[2:3], v[10:11] op_sel_hi:[0,1]
	v_pk_mul_f32 v[12:13], v[2:3], v[12:13] op_sel_hi:[0,1]
	v_addc_co_u32_e32 v29, vcc, 0, v7, vcc
	s_waitcnt vmcnt(3)
	v_pk_fma_f32 v[70:71], v[26:27], v[12:13], v[18:19]
	v_pk_fma_f32 v[72:73], v[24:25], v[10:11], v[16:17]
	v_add_co_u32_e32 v24, vcc, s18, v4
	v_cvt_pk_bf16_f32 v10, v72, v73
	v_cvt_pk_bf16_f32 v11, v70, v71
	global_store_dwordx2 v[50:51], v[10:11], off
	s_nop 0
	v_addc_co_u32_e32 v25, vcc, 0, v5, vcc
	global_load_dwordx2 v[30:31], v[28:29], off
	global_load_dwordx2 v[36:37], v[34:35], off offset:2048
	v_add_co_u32_e32 v38, vcc, s22, v4
	s_mov_b32 s4, 0x37900000
	s_nop 0
	v_addc_co_u32_e32 v39, vcc, 0, v5, vcc
	global_load_dwordx4 v[10:13], v[38:39], off offset:-4096 nt
	v_add_co_u32_e32 v40, vcc, s4, v6
	s_mov_b32 s4, 0x37d00000
	s_nop 0
	v_addc_co_u32_e32 v41, vcc, 0, v7, vcc
	global_load_dwordx2 v[42:43], v[40:41], off
	global_load_dwordx2 v[44:45], v[34:35], off offset:2560
	global_load_dwordx4 v[16:19], v[24:25], off offset:1024 nt
	v_add_co_u32_e32 v46, vcc, s4, v6
	s_waitcnt vmcnt(5)
	v_lshlrev_b32_e32 v56, 16, v30
	v_addc_co_u32_e32 v47, vcc, 0, v7, vcc
	global_load_dwordx2 v[48:49], v[46:47], off
	global_load_dwordx2 v[50:51], v[34:35], off offset:3072
	global_load_dwordx4 v[20:23], v[24:25], off offset:2048 nt
	v_add_co_u32_e32 v86, vcc, s19, v6
	s_waitcnt vmcnt(7)
	v_lshlrev_b32_e32 v54, 16, v36
	v_addc_co_u32_e32 v87, vcc, 0, v7, vcc
	global_load_dwordx2 v[52:53], v[86:87], off
	s_nop 0
	global_load_dwordx2 v[34:35], v[34:35], off offset:3584
	s_nop 0
	global_load_dwordx4 v[24:27], v[24:25], off offset:3072 nt
	v_and_b32_e32 v55, 0xffff0000, v36
	v_lshlrev_b32_e32 v36, 16, v37
	v_and_b32_e32 v37, 0xffff0000, v37
	v_and_b32_e32 v57, 0xffff0000, v30
	v_lshlrev_b32_e32 v30, 16, v31
	v_and_b32_e32 v31, 0xffff0000, v31
	v_pk_mul_f32 v[54:55], v[2:3], v[54:55] op_sel_hi:[0,1]
	v_pk_mul_f32 v[36:37], v[2:3], v[36:37] op_sel_hi:[0,1]
	s_waitcnt vmcnt(9)
	v_pk_fma_f32 v[64:65], v[12:13], v[36:37], v[30:31]
	v_pk_fma_f32 v[66:67], v[10:11], v[54:55], v[56:57]
	s_waitcnt vmcnt(7)
	v_lshlrev_b32_e32 v12, 16, v45
	v_cvt_pk_bf16_f32 v10, v66, v67
	v_cvt_pk_bf16_f32 v11, v64, v65
	global_store_dwordx2 v[28:29], v[10:11], off
	v_lshlrev_b32_e32 v10, 16, v44
	v_and_b32_e32 v11, 0xffff0000, v44
	v_and_b32_e32 v13, 0xffff0000, v45
	v_lshlrev_b32_e32 v28, 16, v42
	v_and_b32_e32 v29, 0xffff0000, v42
	v_lshlrev_b32_e32 v30, 16, v43
	v_and_b32_e32 v31, 0xffff0000, v43
	v_pk_mul_f32 v[10:11], v[2:3], v[10:11] op_sel_hi:[0,1]
	v_pk_mul_f32 v[12:13], v[2:3], v[12:13] op_sel_hi:[0,1]
	s_waitcnt vmcnt(7)
	v_pk_fma_f32 v[60:61], v[18:19], v[12:13], v[30:31]
	v_pk_fma_f32 v[62:63], v[16:17], v[10:11], v[28:29]
	v_add_co_u32_e32 v28, vcc, s20, v6
	v_cvt_pk_bf16_f32 v10, v62, v63
	v_cvt_pk_bf16_f32 v11, v60, v61
	global_store_dwordx2 v[40:41], v[10:11], off
	s_nop 0
	v_addc_co_u32_e32 v29, vcc, 0, v7, vcc
	v_add_co_u32_e32 v36, vcc, s23, v6
	s_waitcnt vmcnt(7)
	v_lshlrev_b32_e32 v16, 16, v48
	s_waitcnt vmcnt(6)
	v_lshlrev_b32_e32 v10, 16, v50
	v_and_b32_e32 v11, 0xffff0000, v50
	v_lshlrev_b32_e32 v12, 16, v51
	v_and_b32_e32 v13, 0xffff0000, v51
	v_and_b32_e32 v17, 0xffff0000, v48
	v_lshlrev_b32_e32 v18, 16, v49
	v_and_b32_e32 v19, 0xffff0000, v49
	v_pk_mul_f32 v[10:11], v[2:3], v[10:11] op_sel_hi:[0,1]
	v_pk_mul_f32 v[12:13], v[2:3], v[12:13] op_sel_hi:[0,1]
	s_waitcnt vmcnt(5)
	v_pk_fma_f32 v[56:57], v[22:23], v[12:13], v[18:19]
	v_pk_fma_f32 v[58:59], v[20:21], v[10:11], v[16:17]
	s_waitcnt vmcnt(3)
	v_lshlrev_b32_e32 v12, 16, v35
	v_cvt_pk_bf16_f32 v10, v58, v59
	v_cvt_pk_bf16_f32 v11, v56, v57
	global_store_dwordx2 v[46:47], v[10:11], off
	v_lshlrev_b32_e32 v10, 16, v34
	v_and_b32_e32 v11, 0xffff0000, v34
	v_and_b32_e32 v13, 0xffff0000, v35
	v_lshlrev_b32_e32 v16, 16, v52
	v_and_b32_e32 v17, 0xffff0000, v52
	v_lshlrev_b32_e32 v18, 16, v53
	v_and_b32_e32 v19, 0xffff0000, v53
	v_pk_mul_f32 v[10:11], v[2:3], v[10:11] op_sel_hi:[0,1]
	v_pk_mul_f32 v[12:13], v[2:3], v[12:13] op_sel_hi:[0,1]
	s_waitcnt vmcnt(3)
	v_pk_fma_f32 v[52:53], v[26:27], v[12:13], v[18:19]
	v_pk_fma_f32 v[54:55], v[24:25], v[10:11], v[16:17]
	v_addc_co_u32_e32 v37, vcc, 0, v7, vcc
	v_cvt_pk_bf16_f32 v10, v54, v55
	v_cvt_pk_bf16_f32 v11, v52, v53
	global_store_dwordx2 v[86:87], v[10:11], off
	global_load_dwordx2 v[30:31], v[28:29], off
	global_load_dwordx2 v[34:35], v[8:9], off
	global_load_dwordx4 v[10:13], v[38:39], off nt
	global_load_dwordx2 v[40:41], v[36:37], off
	global_load_dwordx2 v[42:43], v[8:9], off offset:512
	global_load_dwordx4 v[16:19], v[38:39], off offset:1024 nt
	v_add_co_u32_e32 v50, vcc, s24, v6
	s_waitcnt vmcnt(5)
	v_lshlrev_b32_e32 v44, 16, v30
	v_addc_co_u32_e32 v51, vcc, 0, v7, vcc
	global_load_dwordx2 v[86:87], v[50:51], off
	global_load_dwordx2 v[88:89], v[8:9], off offset:1024
	global_load_dwordx4 v[20:23], v[38:39], off offset:2048 nt
	v_add_co_u32_e32 v90, vcc, s25, v6
	v_and_b32_e32 v45, 0xffff0000, v30
	s_nop 0
	v_addc_co_u32_e32 v91, vcc, 0, v7, vcc
	global_load_dwordx2 v[92:93], v[90:91], off
	global_load_dwordx2 v[94:95], v[8:9], off offset:1536
	global_load_dwordx4 v[24:27], v[38:39], off offset:3072 nt
	s_waitcnt vmcnt(10)
	v_lshlrev_b32_e32 v38, 16, v34
	v_and_b32_e32 v39, 0xffff0000, v34
	v_lshlrev_b32_e32 v34, 16, v35
	v_and_b32_e32 v35, 0xffff0000, v35
	v_lshlrev_b32_e32 v30, 16, v31
	v_and_b32_e32 v31, 0xffff0000, v31
	v_pk_mul_f32 v[38:39], v[2:3], v[38:39] op_sel_hi:[0,1]
	v_pk_mul_f32 v[34:35], v[2:3], v[34:35] op_sel_hi:[0,1]
	s_waitcnt vmcnt(9)
	v_pk_fma_f32 v[46:47], v[12:13], v[34:35], v[30:31]
	v_pk_fma_f32 v[48:49], v[10:11], v[38:39], v[44:45]
	s_waitcnt vmcnt(7)
	v_lshlrev_b32_e32 v12, 16, v43
	v_cvt_pk_bf16_f32 v10, v48, v49
	v_cvt_pk_bf16_f32 v11, v46, v47
	global_store_dwordx2 v[28:29], v[10:11], off
	v_lshlrev_b32_e32 v10, 16, v42
	v_and_b32_e32 v11, 0xffff0000, v42
	v_and_b32_e32 v13, 0xffff0000, v43
	v_lshlrev_b32_e32 v28, 16, v40
	v_and_b32_e32 v29, 0xffff0000, v40
	v_lshlrev_b32_e32 v30, 16, v41
	v_and_b32_e32 v31, 0xffff0000, v41
	v_pk_mul_f32 v[10:11], v[2:3], v[10:11] op_sel_hi:[0,1]
	v_pk_mul_f32 v[12:13], v[2:3], v[12:13] op_sel_hi:[0,1]
	s_waitcnt vmcnt(7)
	v_pk_fma_f32 v[42:43], v[18:19], v[12:13], v[30:31]
	v_pk_fma_f32 v[44:45], v[16:17], v[10:11], v[28:29]
	s_waitcnt vmcnt(6)
	v_lshlrev_b32_e32 v16, 16, v86
	v_cvt_pk_bf16_f32 v10, v44, v45
	v_cvt_pk_bf16_f32 v11, v42, v43
	global_store_dwordx2 v[36:37], v[10:11], off
	s_waitcnt vmcnt(6)
	v_lshlrev_b32_e32 v10, 16, v88
	v_and_b32_e32 v11, 0xffff0000, v88
	v_lshlrev_b32_e32 v12, 16, v89
	v_and_b32_e32 v13, 0xffff0000, v89
	v_and_b32_e32 v17, 0xffff0000, v86
	v_lshlrev_b32_e32 v18, 16, v87
	v_and_b32_e32 v19, 0xffff0000, v87
	v_pk_mul_f32 v[10:11], v[2:3], v[10:11] op_sel_hi:[0,1]
	v_pk_mul_f32 v[12:13], v[2:3], v[12:13] op_sel_hi:[0,1]
	s_waitcnt vmcnt(5)
	v_pk_fma_f32 v[38:39], v[22:23], v[12:13], v[18:19]
	v_pk_fma_f32 v[40:41], v[20:21], v[10:11], v[16:17]
	s_waitcnt vmcnt(3)
	v_lshlrev_b32_e32 v12, 16, v95
	v_cvt_pk_bf16_f32 v10, v40, v41
	v_cvt_pk_bf16_f32 v11, v38, v39
	global_store_dwordx2 v[50:51], v[10:11], off
	v_lshlrev_b32_e32 v10, 16, v94
	v_and_b32_e32 v11, 0xffff0000, v94
	v_and_b32_e32 v13, 0xffff0000, v95
	v_lshlrev_b32_e32 v16, 16, v92
	v_and_b32_e32 v17, 0xffff0000, v92
	v_lshlrev_b32_e32 v18, 16, v93
	v_and_b32_e32 v19, 0xffff0000, v93
	v_pk_mul_f32 v[10:11], v[2:3], v[10:11] op_sel_hi:[0,1]
	v_pk_mul_f32 v[12:13], v[2:3], v[12:13] op_sel_hi:[0,1]
	s_waitcnt vmcnt(3)
	v_pk_fma_f32 v[34:35], v[26:27], v[12:13], v[18:19]
	v_pk_fma_f32 v[36:37], v[24:25], v[10:11], v[16:17]
	v_add_co_u32_e32 v20, vcc, s26, v6
	v_cvt_pk_bf16_f32 v10, v36, v37
	v_cvt_pk_bf16_f32 v11, v34, v35
	global_store_dwordx2 v[90:91], v[10:11], off
	s_nop 0
	v_addc_co_u32_e32 v21, vcc, 0, v7, vcc
	global_load_dwordx2 v[22:23], v[20:21], off
	global_load_dwordx2 v[24:25], v[8:9], off offset:2048
	v_add_co_u32_e32 v4, vcc, s27, v4
	s_waitcnt vmcnt(1)
	v_lshlrev_b32_e32 v30, 16, v22
	v_addc_co_u32_e32 v5, vcc, 0, v5, vcc
	global_load_dwordx4 v[10:13], v[4:5], off nt
	v_add_co_u32_e32 v50, vcc, s28, v6
	s_waitcnt vmcnt(1)
	v_lshlrev_b32_e32 v28, 16, v24
	v_addc_co_u32_e32 v51, vcc, 0, v7, vcc
	global_load_dwordx2 v[26:27], v[50:51], off
	global_load_dwordx2 v[90:91], v[8:9], off offset:2560
	global_load_dwordx4 v[16:19], v[4:5], off offset:1024 nt
	v_add_co_u32_e32 v92, vcc, s29, v6
	v_and_b32_e32 v29, 0xffff0000, v24
	s_nop 0
	v_addc_co_u32_e32 v93, vcc, 0, v7, vcc
	global_load_dwordx2 v[94:95], v[92:93], off
	global_load_dwordx2 v[96:97], v[8:9], off offset:3072
	global_load_dwordx4 v[86:89], v[4:5], off offset:2048 nt
	v_add_co_u32_e32 v98, vcc, s30, v6
	v_lshlrev_b32_e32 v24, 16, v25
	s_nop 0
	v_addc_co_u32_e32 v99, vcc, 0, v7, vcc
	global_load_dwordx2 v[100:101], v[98:99], off
	s_nop 0
	global_load_dwordx2 v[8:9], v[8:9], off offset:3584
	s_nop 0
	global_load_dwordx4 v[4:7], v[4:5], off offset:3072 nt
	v_and_b32_e32 v25, 0xffff0000, v25
	v_and_b32_e32 v31, 0xffff0000, v22
	v_lshlrev_b32_e32 v22, 16, v23
	v_and_b32_e32 v23, 0xffff0000, v23
	v_pk_mul_f32 v[102:103], v[2:3], v[28:29] op_sel_hi:[0,1]
	v_pk_mul_f32 v[24:25], v[2:3], v[24:25] op_sel_hi:[0,1]
	s_waitcnt vmcnt(9)
	v_pk_fma_f32 v[28:29], v[12:13], v[24:25], v[22:23]
	v_pk_fma_f32 v[30:31], v[10:11], v[102:103], v[30:31]
	s_waitcnt vmcnt(8)
	v_lshlrev_b32_e32 v22, 16, v27
	v_cvt_pk_bf16_f32 v10, v30, v31
	v_cvt_pk_bf16_f32 v11, v28, v29
	global_store_dwordx2 v[20:21], v[10:11], off
	s_waitcnt vmcnt(8)
	v_lshlrev_b32_e32 v10, 16, v90
	v_and_b32_e32 v11, 0xffff0000, v90
	v_lshlrev_b32_e32 v12, 16, v91
	v_and_b32_e32 v13, 0xffff0000, v91
	v_lshlrev_b32_e32 v20, 16, v26
	v_and_b32_e32 v21, 0xffff0000, v26
	v_and_b32_e32 v23, 0xffff0000, v27
	v_pk_mul_f32 v[10:11], v[2:3], v[10:11] op_sel_hi:[0,1]
	v_pk_mul_f32 v[12:13], v[2:3], v[12:13] op_sel_hi:[0,1]
	s_waitcnt vmcnt(7)
	v_pk_fma_f32 v[24:25], v[18:19], v[12:13], v[22:23]
	v_pk_fma_f32 v[26:27], v[16:17], v[10:11], v[20:21]
	s_waitcnt vmcnt(5)
	v_lshlrev_b32_e32 v12, 16, v97
	v_cvt_pk_bf16_f32 v10, v26, v27
	v_cvt_pk_bf16_f32 v11, v24, v25
	global_store_dwordx2 v[50:51], v[10:11], off
	v_lshlrev_b32_e32 v10, 16, v96
	v_and_b32_e32 v11, 0xffff0000, v96
	v_and_b32_e32 v13, 0xffff0000, v97
	v_lshlrev_b32_e32 v16, 16, v94
	v_and_b32_e32 v17, 0xffff0000, v94
	v_lshlrev_b32_e32 v18, 16, v95
	v_and_b32_e32 v19, 0xffff0000, v95
	v_pk_mul_f32 v[10:11], v[2:3], v[10:11] op_sel_hi:[0,1]
	v_pk_mul_f32 v[12:13], v[2:3], v[12:13] op_sel_hi:[0,1]
	s_waitcnt vmcnt(5)
	v_pk_fma_f32 v[20:21], v[88:89], v[12:13], v[18:19]
	v_pk_fma_f32 v[22:23], v[86:87], v[10:11], v[16:17]
	s_waitcnt vmcnt(4)
	v_lshlrev_b32_e32 v12, 16, v100
	v_cvt_pk_bf16_f32 v10, v22, v23
	v_cvt_pk_bf16_f32 v11, v20, v21
	global_store_dwordx2 v[92:93], v[10:11], off
	s_waitcnt vmcnt(4)
	v_lshlrev_b32_e32 v10, 16, v8
	v_and_b32_e32 v11, 0xffff0000, v8
	v_lshlrev_b32_e32 v8, 16, v9
	v_and_b32_e32 v9, 0xffff0000, v9
	v_and_b32_e32 v13, 0xffff0000, v100
	v_lshlrev_b32_e32 v16, 16, v101
	v_and_b32_e32 v17, 0xffff0000, v101
	v_pk_mul_f32 v[10:11], v[2:3], v[10:11] op_sel_hi:[0,1]
	v_pk_mul_f32 v[8:9], v[2:3], v[8:9] op_sel_hi:[0,1]
	s_waitcnt vmcnt(3)
	v_pk_fma_f32 v[16:17], v[6:7], v[8:9], v[16:17]
	v_pk_fma_f32 v[18:19], v[4:5], v[10:11], v[12:13]
	v_pk_mul_f32 v[6:7], v[82:83], v[82:83]
	v_cvt_pk_bf16_f32 v4, v18, v19
	v_cvt_pk_bf16_f32 v5, v16, v17
	global_store_dwordx2 v[98:99], v[4:5], off
	v_pk_mul_f32 v[4:5], v[68:69], v[68:69]
	v_mul_f32_e32 v2, v72, v72
	v_pk_mov_b32 v[8:9], v[6:7], v[4:5] op_sel:[1,0]
	v_mov_b32_e32 v7, v5
	v_pk_add_f32 v[4:5], v[8:9], v[6:7]
	v_pk_mul_f32 v[6:7], v[78:79], v[78:79]
	v_pk_mul_f32 v[8:9], v[80:81], v[80:81]
	v_pk_add_f32 v[4:5], v[4:5], v[4:5] op_sel:[0,1] op_sel_hi:[1,0]
	v_pk_mov_b32 v[10:11], v[8:9], v[6:7] op_sel:[1,0]
	v_mov_b32_e32 v9, v7
	v_pk_add_f32 v[6:7], v[10:11], v[8:9]
	v_mul_f32_e32 v8, v73, v73
	v_pk_add_f32 v[6:7], v[6:7], v[6:7] op_sel:[0,1] op_sel_hi:[1,0]
	v_mov_b32_e32 v5, v2
	v_mov_b32_e32 v7, v8
	v_mul_f32_e32 v2, v77, v77
	v_mul_f32_e32 v9, v70, v70
	v_pk_add_f32 v[4:5], v[4:5], v[6:7]
	v_pk_fma_f32 v[6:7], v[76:77], v[76:77], v[2:3] op_sel_hi:[1,1,0]
	v_mul_f32_e32 v2, v75, v75
	v_mul_f32_e32 v10, v71, v71
	v_mov_b32_e32 v7, v9
	v_pk_fma_f32 v[8:9], v[74:75], v[74:75], v[2:3] op_sel_hi:[1,1,0]
	v_mul_f32_e32 v2, v58, v58
	v_mov_b32_e32 v9, v10
	v_pk_add_f32 v[6:7], v[6:7], v[8:9]
	v_pk_mul_f32 v[8:9], v[66:67], v[66:67]
	v_pk_add_f32 v[4:5], v[4:5], v[6:7]
	v_pk_mul_f32 v[6:7], v[64:65], v[64:65]
	v_pk_add_f32 v[4:5], v[4:5], v[4:5] op_sel:[0,1] op_sel_hi:[1,0]
	v_pk_mov_b32 v[10:11], v[8:9], v[6:7] op_sel:[1,0]
	v_mov_b32_e32 v9, v7
	v_pk_add_f32 v[6:7], v[10:11], v[8:9]
	v_mul_f32_e32 v8, v59, v59
	v_pk_add_f32 v[6:7], v[6:7], v[6:7] op_sel:[0,1] op_sel_hi:[1,0]
	v_mov_b32_e32 v5, v2
	v_mov_b32_e32 v7, v8
	v_mul_f32_e32 v2, v63, v63
	v_mul_f32_e32 v9, v56, v56
	v_pk_add_f32 v[4:5], v[4:5], v[6:7]
	v_pk_fma_f32 v[6:7], v[62:63], v[62:63], v[2:3] op_sel_hi:[1,1,0]
	v_mul_f32_e32 v2, v61, v61
	v_mul_f32_e32 v10, v57, v57
	v_mov_b32_e32 v7, v9
	v_pk_fma_f32 v[8:9], v[60:61], v[60:61], v[2:3] op_sel_hi:[1,1,0]
	v_mul_f32_e32 v2, v44, v44
	v_mov_b32_e32 v9, v10
	v_pk_add_f32 v[6:7], v[6:7], v[8:9]
	v_pk_mul_f32 v[8:9], v[54:55], v[54:55]
	v_pk_add_f32 v[4:5], v[4:5], v[6:7]
	v_pk_mul_f32 v[6:7], v[52:53], v[52:53]
	v_pk_add_f32 v[4:5], v[4:5], v[4:5] op_sel:[0,1] op_sel_hi:[1,0]
	v_pk_mov_b32 v[10:11], v[8:9], v[6:7] op_sel:[1,0]
	v_mov_b32_e32 v9, v7
	v_pk_add_f32 v[6:7], v[10:11], v[8:9]
	v_mul_f32_e32 v8, v45, v45
	v_pk_add_f32 v[6:7], v[6:7], v[6:7] op_sel:[0,1] op_sel_hi:[1,0]
	v_mov_b32_e32 v5, v2
	v_mov_b32_e32 v7, v8
	v_mul_f32_e32 v2, v49, v49
	v_mul_f32_e32 v9, v42, v42
	v_pk_add_f32 v[4:5], v[4:5], v[6:7]
	v_pk_fma_f32 v[6:7], v[48:49], v[48:49], v[2:3] op_sel_hi:[1,1,0]
	v_mul_f32_e32 v2, v47, v47
	v_mul_f32_e32 v10, v43, v43
	v_mov_b32_e32 v7, v9
	v_pk_fma_f32 v[8:9], v[46:47], v[46:47], v[2:3] op_sel_hi:[1,1,0]
	v_mul_f32_e32 v2, v30, v30
	v_mov_b32_e32 v9, v10
	v_pk_add_f32 v[6:7], v[6:7], v[8:9]
	v_pk_mul_f32 v[8:9], v[40:41], v[40:41]
	v_pk_add_f32 v[4:5], v[4:5], v[6:7]
	v_pk_mul_f32 v[6:7], v[38:39], v[38:39]
	v_pk_add_f32 v[4:5], v[4:5], v[4:5] op_sel:[0,1] op_sel_hi:[1,0]
	v_pk_mov_b32 v[10:11], v[8:9], v[6:7] op_sel:[1,0]
	v_mov_b32_e32 v9, v7
	v_pk_add_f32 v[6:7], v[10:11], v[8:9]
	v_mul_f32_e32 v8, v31, v31
	v_pk_add_f32 v[6:7], v[6:7], v[6:7] op_sel:[0,1] op_sel_hi:[1,0]
	v_mov_b32_e32 v5, v2
	v_mov_b32_e32 v7, v8
	v_mul_f32_e32 v2, v37, v37
	v_mul_f32_e32 v9, v28, v28
	v_pk_add_f32 v[4:5], v[4:5], v[6:7]
	v_pk_fma_f32 v[6:7], v[36:37], v[36:37], v[2:3] op_sel_hi:[1,1,0]
	v_mul_f32_e32 v2, v35, v35
	v_mul_f32_e32 v10, v29, v29
	v_mov_b32_e32 v7, v9
	v_pk_fma_f32 v[8:9], v[34:35], v[34:35], v[2:3] op_sel_hi:[1,1,0]
	v_mul_f32_e32 v2, v18, v18
	v_mov_b32_e32 v9, v10
	v_pk_add_f32 v[6:7], v[6:7], v[8:9]
	v_pk_mul_f32 v[8:9], v[26:27], v[26:27]
	v_pk_add_f32 v[4:5], v[4:5], v[6:7]
	v_pk_mul_f32 v[6:7], v[24:25], v[24:25]
	v_pk_add_f32 v[4:5], v[4:5], v[4:5] op_sel:[0,1] op_sel_hi:[1,0]
	v_pk_mov_b32 v[10:11], v[8:9], v[6:7] op_sel:[1,0]
	v_mov_b32_e32 v9, v7
	v_pk_add_f32 v[6:7], v[10:11], v[8:9]
	v_mul_f32_e32 v8, v19, v19
	v_pk_add_f32 v[6:7], v[6:7], v[6:7] op_sel:[0,1] op_sel_hi:[1,0]
	v_mov_b32_e32 v5, v2
	v_mov_b32_e32 v7, v8
	v_mul_f32_e32 v2, v23, v23
	v_mul_f32_e32 v9, v16, v16
	v_pk_add_f32 v[4:5], v[4:5], v[6:7]
	v_pk_fma_f32 v[6:7], v[22:23], v[22:23], v[2:3] op_sel_hi:[1,1,0]
	v_mul_f32_e32 v2, v21, v21
	v_mul_f32_e32 v10, v17, v17
	v_mov_b32_e32 v7, v9
	v_pk_fma_f32 v[8:9], v[20:21], v[20:21], v[2:3] op_sel_hi:[1,1,0]
	v_lshl_add_u64 v[50:51], s[2:3], 0, v[14:15]
	v_mov_b32_e32 v9, v10
	v_pk_add_f32 v[6:7], v[6:7], v[8:9]
	s_nop 0
	v_pk_add_f32 v[4:5], v[4:5], v[6:7]
	s_nop 0
	v_add_f32_e32 v2, v4, v5
	ds_bpermute_b32 v4, v1, v2
	s_waitcnt lgkmcnt(0)
	v_add_f32_e32 v2, v2, v4
	ds_bpermute_b32 v4, v201, v2
	s_waitcnt lgkmcnt(0)
	v_add_f32_e32 v2, v2, v4
	ds_bpermute_b32 v4, v205, v2
	s_waitcnt lgkmcnt(0)
	v_add_f32_e32 v2, v2, v4
	ds_bpermute_b32 v4, v211, v2
	s_waitcnt lgkmcnt(0)
	v_add_f32_e32 v2, v2, v4
	ds_bpermute_b32 v4, v218, v2
	s_waitcnt lgkmcnt(0)
	v_add_f32_e32 v2, v2, v4
	ds_bpermute_b32 v4, v219, v2
	s_waitcnt lgkmcnt(0)
	v_add_f32_e32 v2, v2, v4
	v_fmamk_f32 v2, v2, 0x39800000, v33
	v_rsq_f32_e32 v32, v2
	global_load_dwordx4 v[86:89], v14, s[2:3]
	global_load_dwordx4 v[10:13], v14, s[2:3] offset:1024
	global_load_dwordx4 v[6:9], v14, s[2:3] offset:2048
	global_load_dwordx4 v[2:5], v14, s[2:3] offset:3072
	v_and_or_b32 v14, v84, s31, v85
	v_pk_mul_f32 v[82:83], v[82:83], v[32:33] op_sel_hi:[1,0]
	v_pk_mul_f32 v[68:69], v[68:69], v[32:33] op_sel_hi:[1,0]
	v_pk_mul_f32 v[80:81], v[80:81], v[32:33] op_sel_hi:[1,0]
	v_pk_mul_f32 v[78:79], v[78:79], v[32:33] op_sel_hi:[1,0]
	v_pk_mul_f32 v[64:65], v[64:65], v[32:33] op_sel_hi:[1,0]
	v_pk_mul_f32 v[30:31], v[30:31], v[32:33] op_sel_hi:[1,0]
	v_pk_mul_f32 v[28:29], v[28:29], v[32:33] op_sel_hi:[1,0]
	s_waitcnt vmcnt(3)
	v_pk_mul_f32 v[82:83], v[86:87], v[82:83]
	v_mov_b32_e32 v86, v15
	v_cvt_pk_fp8_f32 v86, v82, v83
	v_pk_mul_f32 v[68:69], v[88:89], v[68:69]
	s_waitcnt vmcnt(2)
	v_pk_mul_f32 v[10:11], v[10:11], v[80:81]
	v_pk_mul_f32 v[12:13], v[12:13], v[78:79]
	v_cvt_pk_fp8_f32 v86, v68, v69 op_sel:[0,0,1]
	v_lshl_add_u64 v[68:69], s[16:17], 0, v[14:15]
	v_mov_b32_e32 v14, v15
	v_cvt_pk_fp8_f32 v14, v10, v11
	v_add_co_u32_e32 v82, vcc, s33, v68
	v_cvt_pk_fp8_f32 v14, v12, v13 op_sel:[0,0,1]
	s_nop 0
	v_addc_co_u32_e32 v83, vcc, 0, v69, vcc
	v_add_co_u32_e32 v10, vcc, s34, v68
	v_pk_mul_f32 v[12:13], v[74:75], v[32:33] op_sel_hi:[1,0]
	s_nop 0
	v_addc_co_u32_e32 v11, vcc, 0, v69, vcc
	global_store_dword v[10:11], v14, off
	v_pk_mul_f32 v[10:11], v[76:77], v[32:33] op_sel_hi:[1,0]
	s_waitcnt vmcnt(2)
	v_pk_mul_f32 v[8:9], v[8:9], v[12:13]
	v_pk_mul_f32 v[6:7], v[6:7], v[10:11]
	v_mov_b32_e32 v10, v15
	v_cvt_pk_fp8_f32 v10, v6, v7
	v_add_co_u32_e32 v6, vcc, s35, v68
	global_store_dword v[82:83], v86, off
	v_cvt_pk_fp8_f32 v10, v8, v9 op_sel:[0,0,1]
	v_addc_co_u32_e32 v7, vcc, 0, v69, vcc
	v_pk_mul_f32 v[8:9], v[70:71], v[32:33] op_sel_hi:[1,0]
	global_store_dword v[6:7], v10, off
	v_pk_mul_f32 v[6:7], v[72:73], v[32:33] op_sel_hi:[1,0]
	s_waitcnt vmcnt(3)
	v_pk_mul_f32 v[4:5], v[4:5], v[8:9]
	v_pk_mul_f32 v[2:3], v[2:3], v[6:7]
	v_mov_b32_e32 v6, v15
	v_cvt_pk_fp8_f32 v6, v2, v3
	v_add_co_u32_e32 v2, vcc, s36, v68
	v_mov_b32_e32 v14, v15
	v_cvt_pk_fp8_f32 v6, v4, v5 op_sel:[0,0,1]
	v_addc_co_u32_e32 v3, vcc, 0, v69, vcc
	v_add_co_u32_e32 v4, vcc, s18, v50
	global_store_dword v[2:3], v6, off
	s_nop 0
	v_addc_co_u32_e32 v5, vcc, 0, v51, vcc
	v_add_co_u32_e32 v2, vcc, s22, v50
	s_nop 1
	v_addc_co_u32_e32 v3, vcc, 0, v51, vcc
	global_load_dwordx4 v[6:9], v[2:3], off offset:-4096
	global_load_dwordx4 v[10:13], v[4:5], off offset:1024
	global_load_dwordx4 v[70:73], v[4:5], off offset:2048
	global_load_dwordx4 v[74:77], v[4:5], off offset:3072
	v_pk_mul_f32 v[4:5], v[66:67], v[32:33] op_sel_hi:[1,0]
	s_waitcnt vmcnt(3)
	v_pk_mul_f32 v[8:9], v[64:65], v[8:9]
	v_pk_mul_f32 v[4:5], v[4:5], v[6:7]
	v_mov_b32_e32 v6, v15
	v_cvt_pk_fp8_f32 v6, v4, v5
	v_add_co_u32_e32 v4, vcc, s37, v68
	v_cvt_pk_fp8_f32 v6, v8, v9 op_sel:[0,0,1]
	s_nop 0
	v_addc_co_u32_e32 v5, vcc, 0, v69, vcc
	v_mov_b32_e32 v8, v15
	global_store_dword v[4:5], v6, off
	v_pk_mul_f32 v[4:5], v[62:63], v[32:33] op_sel_hi:[1,0]
	v_pk_mul_f32 v[6:7], v[60:61], v[32:33] op_sel_hi:[1,0]
	s_waitcnt vmcnt(3)
	v_pk_mul_f32 v[4:5], v[4:5], v[10:11]
	v_pk_mul_f32 v[6:7], v[6:7], v[12:13]
	v_cvt_pk_fp8_f32 v8, v4, v5
	v_add_co_u32_e32 v4, vcc, s38, v68
	v_pk_mul_f32 v[12:13], v[46:47], v[32:33] op_sel_hi:[1,0]
	v_cvt_pk_fp8_f32 v8, v6, v7 op_sel:[0,0,1]
	v_addc_co_u32_e32 v5, vcc, 0, v69, vcc
	v_pk_mul_f32 v[6:7], v[56:57], v[32:33] op_sel_hi:[1,0]
	global_store_dword v[4:5], v8, off
	v_pk_mul_f32 v[4:5], v[58:59], v[32:33] op_sel_hi:[1,0]
	v_mov_b32_e32 v8, v15
	s_waitcnt vmcnt(3)
	v_pk_mul_f32 v[4:5], v[4:5], v[70:71]
	v_pk_mul_f32 v[6:7], v[6:7], v[72:73]
	v_cvt_pk_fp8_f32 v8, v4, v5
	v_add_co_u32_e32 v4, vcc, s39, v68
	v_cvt_pk_fp8_f32 v8, v6, v7 op_sel:[0,0,1]
	s_nop 0
	v_addc_co_u32_e32 v5, vcc, 0, v69, vcc
	v_pk_mul_f32 v[6:7], v[52:53], v[32:33] op_sel_hi:[1,0]
	global_store_dword v[4:5], v8, off
	v_pk_mul_f32 v[4:5], v[54:55], v[32:33] op_sel_hi:[1,0]
	v_mov_b32_e32 v8, v15
	s_waitcnt vmcnt(3)
	v_pk_mul_f32 v[4:5], v[4:5], v[74:75]
	v_pk_mul_f32 v[6:7], v[6:7], v[76:77]
	v_cvt_pk_fp8_f32 v8, v4, v5
	v_add_co_u32_e32 v4, vcc, s40, v68
	v_cvt_pk_fp8_f32 v8, v6, v7 op_sel:[0,0,1]
	s_nop 0
	v_addc_co_u32_e32 v5, vcc, 0, v69, vcc
	global_store_dword v[4:5], v8, off
	global_load_dwordx4 v[4:7], v[2:3], off
	global_load_dwordx4 v[8:11], v[2:3], off offset:1024
	global_load_dwordx4 v[52:55], v[2:3], off offset:2048
	global_load_dwordx4 v[56:59], v[2:3], off offset:3072
	v_pk_mul_f32 v[2:3], v[48:49], v[32:33] op_sel_hi:[1,0]
	s_waitcnt vmcnt(3)
	v_pk_mul_f32 v[6:7], v[12:13], v[6:7]
	v_pk_mul_f32 v[2:3], v[2:3], v[4:5]
	v_mov_b32_e32 v4, v15
	v_cvt_pk_fp8_f32 v4, v2, v3
	v_add_co_u32_e32 v2, vcc, s41, v68
	v_cvt_pk_fp8_f32 v4, v6, v7 op_sel:[0,0,1]
	s_nop 0
	v_addc_co_u32_e32 v3, vcc, 0, v69, vcc
	v_mov_b32_e32 v6, v15
	global_store_dword v[2:3], v4, off
	v_pk_mul_f32 v[2:3], v[44:45], v[32:33] op_sel_hi:[1,0]
	v_pk_mul_f32 v[4:5], v[42:43], v[32:33] op_sel_hi:[1,0]
	s_waitcnt vmcnt(3)
	v_pk_mul_f32 v[2:3], v[2:3], v[8:9]
	v_pk_mul_f32 v[4:5], v[4:5], v[10:11]
	v_cvt_pk_fp8_f32 v6, v2, v3
	v_add_co_u32_e32 v2, vcc, s42, v68
	v_cvt_pk_fp8_f32 v6, v4, v5 op_sel:[0,0,1]
	s_nop 0
	v_addc_co_u32_e32 v3, vcc, 0, v69, vcc
	v_pk_mul_f32 v[4:5], v[38:39], v[32:33] op_sel_hi:[1,0]
	global_store_dword v[2:3], v6, off
	v_pk_mul_f32 v[2:3], v[40:41], v[32:33] op_sel_hi:[1,0]
	v_mov_b32_e32 v6, v15
	s_waitcnt vmcnt(3)
	v_pk_mul_f32 v[2:3], v[2:3], v[52:53]
	v_pk_mul_f32 v[4:5], v[4:5], v[54:55]
	v_cvt_pk_fp8_f32 v6, v2, v3
	v_add_co_u32_e32 v2, vcc, s43, v68
	v_cvt_pk_fp8_f32 v6, v4, v5 op_sel:[0,0,1]
	s_nop 0
	v_addc_co_u32_e32 v3, vcc, 0, v69, vcc
	v_pk_mul_f32 v[4:5], v[34:35], v[32:33] op_sel_hi:[1,0]
	global_store_dword v[2:3], v6, off
	v_pk_mul_f32 v[2:3], v[36:37], v[32:33] op_sel_hi:[1,0]
	v_mov_b32_e32 v6, v15
	s_waitcnt vmcnt(3)
	v_pk_mul_f32 v[2:3], v[2:3], v[56:57]
	v_pk_mul_f32 v[4:5], v[4:5], v[58:59]
	v_cvt_pk_fp8_f32 v6, v2, v3
	v_add_co_u32_e32 v2, vcc, s44, v68
	v_cvt_pk_fp8_f32 v6, v4, v5 op_sel:[0,0,1]
	s_nop 0
	v_addc_co_u32_e32 v3, vcc, 0, v69, vcc
	v_add_co_u32_e32 v34, vcc, s27, v50
	global_store_dword v[2:3], v6, off
	s_nop 0
	v_addc_co_u32_e32 v35, vcc, 0, v51, vcc
	global_load_dwordx4 v[2:5], v[34:35], off
	global_load_dwordx4 v[6:9], v[34:35], off offset:1024
	global_load_dwordx4 v[10:13], v[34:35], off offset:2048
	s_nop 0
	global_load_dwordx4 v[34:37], v[34:35], off offset:3072
	s_waitcnt vmcnt(3)
	v_pk_mul_f32 v[2:3], v[30:31], v[2:3]
	s_nop 0
	v_cvt_pk_fp8_f32 v14, v2, v3
	v_pk_mul_f32 v[4:5], v[28:29], v[4:5]
	v_add_co_u32_e32 v2, vcc, s45, v68
	v_cvt_pk_fp8_f32 v14, v4, v5 op_sel:[0,0,1]
	s_nop 0
	v_addc_co_u32_e32 v3, vcc, 0, v69, vcc
	v_pk_mul_f32 v[4:5], v[24:25], v[32:33] op_sel_hi:[1,0]
	global_store_dword v[2:3], v14, off
	v_pk_mul_f32 v[2:3], v[26:27], v[32:33] op_sel_hi:[1,0]
	s_waitcnt vmcnt(3)
	v_pk_mul_f32 v[4:5], v[4:5], v[8:9]
	v_pk_mul_f32 v[2:3], v[2:3], v[6:7]
	v_mov_b32_e32 v6, v15
	v_cvt_pk_fp8_f32 v6, v2, v3
	v_add_co_u32_e32 v2, vcc, s46, v68
	v_cvt_pk_fp8_f32 v6, v4, v5 op_sel:[0,0,1]
	s_nop 0
	v_addc_co_u32_e32 v3, vcc, 0, v69, vcc
	v_pk_mul_f32 v[4:5], v[20:21], v[32:33] op_sel_hi:[1,0]
	global_store_dword v[2:3], v6, off
	v_pk_mul_f32 v[2:3], v[22:23], v[32:33] op_sel_hi:[1,0]
	v_mov_b32_e32 v6, v15
	s_waitcnt vmcnt(3)
	v_pk_mul_f32 v[2:3], v[2:3], v[10:11]
	v_pk_mul_f32 v[4:5], v[4:5], v[12:13]
	v_cvt_pk_fp8_f32 v6, v2, v3
	v_add_co_u32_e32 v2, vcc, s47, v68
	v_cvt_pk_fp8_f32 v6, v4, v5 op_sel:[0,0,1]
	s_nop 0
	v_addc_co_u32_e32 v3, vcc, 0, v69, vcc
	v_pk_mul_f32 v[4:5], v[16:17], v[32:33] op_sel_hi:[1,0]
	global_store_dword v[2:3], v6, off
	v_pk_mul_f32 v[2:3], v[18:19], v[32:33] op_sel_hi:[1,0]
	v_mov_b32_e32 v6, v15
	s_waitcnt vmcnt(3)
	v_pk_mul_f32 v[2:3], v[2:3], v[34:35]
	v_pk_mul_f32 v[4:5], v[4:5], v[36:37]
	v_cvt_pk_fp8_f32 v6, v2, v3
	v_add_co_u32_e32 v2, vcc, s48, v68
	v_cvt_pk_fp8_f32 v6, v4, v5 op_sel:[0,0,1]
	s_nop 0
	v_addc_co_u32_e32 v3, vcc, 0, v69, vcc
	global_store_dword v[2:3], v6, off
	s_cbranch_scc0 .LBB0_2262

.LBB0_2791:
	s_mov_b32 s40, 25
	s_ashr_i32 s41, s40, 31
	s_lshl_b64 s[40:41], s[40:41], 3
	s_add_u32 s40, s68, s40
	s_addc_u32 s41, s69, s41
	v_mov_b32_e32 v2, v0
	s_add_u32 s42, s70, s0
	s_load_dwordx2 s[40:41], s[40:41], 0x0
	s_addc_u32 s43, s71, s1
	v_and_b32_e32 v4, 63, v2
	v_lshlrev_b32_e32 v3, 16, v2
	v_and_b32_e32 v2, 15, v2
	s_add_u32 s44, s70, s2
	v_lshlrev_b32_e32 v5, 2, v4
	v_lshlrev_b32_e32 v18, 3, v4
	v_lshlrev_b32_e32 v2, 3, v2
	s_addc_u32 s45, s71, s3
	global_load_dword v45, v5, s[42:43]
	v_and_or_b32 v26, v3, s16, v2
	v_lshl_add_u64 v[2:3], s[44:45], 0, v[18:19]
	v_add_co_u32_e32 v24, vcc, s18, v2
	v_lshlrev_b32_e32 v18, 4, v4
	s_nop 0
	v_addc_co_u32_e32 v25, vcc, 0, v3, vcc
	v_add_co_u32_e32 v22, vcc, s28, v2
	s_waitcnt lgkmcnt(0)
	v_lshl_add_u64 v[34:35], s[40:41], 0, v[18:19]
	v_addc_co_u32_e32 v23, vcc, 0, v3, vcc
	global_load_dwordx4 v[2:5], v18, s[40:41]
	global_load_dwordx4 v[6:9], v18, s[40:41] offset:1024
	global_load_dwordx4 v[10:13], v18, s[40:41] offset:2048
	global_load_dwordx4 v[14:17], v18, s[40:41] offset:3072
	global_load_dwordx2 v[30:31], v[22:23], off offset:-4096
	s_add_u32 s42, s70, s12
	v_add_co_u32_e32 v36, vcc, s23, v34
	v_mov_b32_e32 v27, v19
	s_addc_u32 s43, s71, s13
	v_addc_co_u32_e32 v37, vcc, 0, v35, vcc
	v_lshl_add_u64 v[32:33], s[42:43], 0, v[26:27]
	v_add_co_u32_e32 v26, vcc, s29, v34
	v_lshl_add_u64 v[20:21], s[6:7], 0, v[18:19]
	s_nop 0
	v_addc_co_u32_e32 v27, vcc, 0, v35, vcc
	v_add_co_u32_e32 v38, vcc, s23, v20
	s_add_i32 s72, s72, s74
	s_nop 0
	v_addc_co_u32_e32 v39, vcc, 0, v21, vcc
	v_add_co_u32_e32 v28, vcc, s29, v20
	s_add_u32 s2, s2, s4
	s_nop 0
	v_addc_co_u32_e32 v29, vcc, 0, v21, vcc
	v_add_co_u32_e32 v34, vcc, s35, v34
	s_addc_u32 s3, s3, s5
	s_nop 0
	v_addc_co_u32_e32 v35, vcc, 0, v35, vcc
	v_add_co_u32_e32 v46, vcc, s17, v32
	s_nop 1
	v_addc_co_u32_e32 v47, vcc, 0, v33, vcc
	v_add_co_u32_e32 v48, vcc, s19, v32
	s_nop 1
	v_addc_co_u32_e32 v49, vcc, 0, v33, vcc
	v_add_co_u32_e32 v50, vcc, s20, v32
	s_nop 1
	v_addc_co_u32_e32 v51, vcc, 0, v33, vcc
	v_add_co_u32_e32 v52, vcc, s21, v32
	s_nop 1
	v_addc_co_u32_e32 v53, vcc, 0, v33, vcc
	global_load_dwordx2 v[72:73], v[46:47], off
	global_load_dwordx2 v[74:75], v[24:25], off offset:512
	global_load_dwordx2 v[76:77], v[48:49], off
	global_load_dwordx2 v[78:79], v[24:25], off offset:1024
	global_load_dwordx2 v[80:81], v[50:51], off
	global_load_dwordx2 v[82:83], v[52:53], off
	global_load_dwordx2 v[84:85], v[24:25], off offset:1536
	v_add_co_u32_e32 v54, vcc, s22, v32
	s_waitcnt vmcnt(12)
	ds_bpermute_b32 v50, v1, v45
	v_addc_co_u32_e32 v55, vcc, 0, v33, vcc
	v_add_co_u32_e32 v56, vcc, s24, v32
	s_waitcnt vmcnt(7)
	v_lshlrev_b32_e32 v46, 16, v30
	v_and_b32_e32 v47, 0xffff0000, v30
	s_waitcnt lgkmcnt(0)
	v_add_f32_e32 v30, v45, v50
	v_lshlrev_b32_e32 v48, 16, v31
	v_and_b32_e32 v49, 0xffff0000, v31
	ds_bpermute_b32 v31, v201, v30
	v_addc_co_u32_e32 v57, vcc, 0, v33, vcc
	v_add_co_u32_e32 v58, vcc, s25, v32
	s_waitcnt lgkmcnt(0)
	v_add_f32_e32 v30, v30, v31
	ds_bpermute_b32 v31, v205, v30
	v_addc_co_u32_e32 v59, vcc, 0, v33, vcc
	v_add_co_u32_e32 v60, vcc, s26, v32
	s_waitcnt lgkmcnt(0)
	v_add_f32_e32 v30, v30, v31
	ds_bpermute_b32 v31, v211, v30
	v_addc_co_u32_e32 v61, vcc, 0, v33, vcc
	v_add_co_u32_e32 v62, vcc, s27, v32
	s_waitcnt lgkmcnt(0)
	v_add_f32_e32 v30, v30, v31
	ds_bpermute_b32 v31, v218, v30
	v_addc_co_u32_e32 v63, vcc, 0, v33, vcc
	v_add_co_u32_e32 v64, vcc, s30, v32
	s_waitcnt lgkmcnt(0)
	v_add_f32_e32 v30, v30, v31
	ds_bpermute_b32 v31, v219, v30
	v_addc_co_u32_e32 v65, vcc, 0, v33, vcc
	v_add_co_u32_e32 v66, vcc, s31, v32
	s_waitcnt lgkmcnt(0)
	v_add_f32_e32 v30, v30, v31
	v_fmamk_f32 v30, v30, 0x39800000, v44
	v_rsq_f32_e32 v30, v30
	v_addc_co_u32_e32 v67, vcc, 0, v33, vcc
	v_add_co_u32_e32 v68, vcc, s33, v32
	v_mul_f32_e32 v30, 0.5, v30
	v_pk_mul_f32 v[46:47], v[30:31], v[46:47] op_sel_hi:[0,1]
	s_waitcnt vmcnt(6)
	v_lshlrev_b32_e32 v50, 16, v72
	v_and_b32_e32 v51, 0xffff0000, v72
	v_lshlrev_b32_e32 v52, 16, v73
	v_and_b32_e32 v53, 0xffff0000, v73
	s_waitcnt vmcnt(5)
	v_lshlrev_b32_e32 v72, 16, v74
	v_and_b32_e32 v73, 0xffff0000, v74
	v_lshlrev_b32_e32 v74, 16, v75
	v_and_b32_e32 v75, 0xffff0000, v75
	s_waitcnt vmcnt(3)
	v_lshlrev_b32_e32 v88, 16, v78
	v_and_b32_e32 v89, 0xffff0000, v78
	v_lshlrev_b32_e32 v78, 16, v79
	v_and_b32_e32 v79, 0xffff0000, v79
	s_waitcnt vmcnt(0)
	v_lshlrev_b32_e32 v92, 16, v84
	v_and_b32_e32 v93, 0xffff0000, v84
	v_lshlrev_b32_e32 v84, 16, v85
	v_and_b32_e32 v85, 0xffff0000, v85
	v_pk_mul_f32 v[48:49], v[30:31], v[48:49] op_sel_hi:[0,1]
	v_lshlrev_b32_e32 v86, 16, v76
	v_and_b32_e32 v87, 0xffff0000, v76
	v_lshlrev_b32_e32 v76, 16, v77
	v_and_b32_e32 v77, 0xffff0000, v77
	v_lshlrev_b32_e32 v90, 16, v80
	v_and_b32_e32 v91, 0xffff0000, v80
	v_lshlrev_b32_e32 v80, 16, v81
	v_and_b32_e32 v81, 0xffff0000, v81
	v_lshlrev_b32_e32 v94, 16, v82
	v_and_b32_e32 v95, 0xffff0000, v82
	v_lshlrev_b32_e32 v82, 16, v83
	v_and_b32_e32 v83, 0xffff0000, v83
	v_pk_mul_f32 v[72:73], v[30:31], v[72:73] op_sel_hi:[0,1]
	v_pk_mul_f32 v[74:75], v[30:31], v[74:75] op_sel_hi:[0,1]
	v_pk_mul_f32 v[88:89], v[30:31], v[88:89] op_sel_hi:[0,1]
	v_pk_mul_f32 v[78:79], v[30:31], v[78:79] op_sel_hi:[0,1]
	v_pk_mul_f32 v[92:93], v[30:31], v[92:93] op_sel_hi:[0,1]
	v_pk_mul_f32 v[84:85], v[30:31], v[84:85] op_sel_hi:[0,1]
	v_pk_fma_f32 v[4:5], v[4:5], v[48:49], v[52:53]
	v_pk_fma_f32 v[2:3], v[2:3], v[46:47], v[50:51]
	v_pk_fma_f32 v[8:9], v[8:9], v[74:75], v[76:77]
	v_pk_fma_f32 v[6:7], v[6:7], v[72:73], v[86:87]
	v_pk_fma_f32 v[12:13], v[12:13], v[78:79], v[80:81]
	v_pk_fma_f32 v[10:11], v[10:11], v[88:89], v[90:91]
	v_pk_fma_f32 v[16:17], v[16:17], v[84:85], v[82:83]
	v_pk_fma_f32 v[14:15], v[14:15], v[92:93], v[94:95]
	global_store_dwordx4 v18, v[2:5], s[6:7]
	global_store_dwordx4 v18, v[6:9], s[6:7] offset:1024
	global_store_dwordx4 v18, v[10:13], s[6:7] offset:2048
	global_store_dwordx4 v18, v[14:17], s[6:7] offset:3072
	global_load_dwordx2 v[46:47], v[24:25], off offset:2048
	global_load_dwordx2 v[48:49], v[54:55], off
	global_load_dwordx2 v[50:51], v[24:25], off offset:2560
	global_load_dwordx2 v[52:53], v[56:57], off
	global_load_dwordx2 v[72:73], v[24:25], off offset:3072
	global_load_dwordx2 v[74:75], v[58:59], off
	global_load_dwordx2 v[76:77], v[24:25], off offset:3584
	global_load_dwordx2 v[78:79], v[60:61], off
	global_load_dwordx4 v[2:5], v[26:27], off offset:-4096 nt
	global_load_dwordx4 v[6:9], v[36:37], off offset:1024 nt
	global_load_dwordx4 v[10:13], v[36:37], off offset:2048 nt
	global_load_dwordx4 v[14:17], v[36:37], off offset:3072 nt
	v_addc_co_u32_e32 v69, vcc, 0, v33, vcc
	v_add_co_u32_e32 v40, vcc, s34, v32
	s_add_u32 s6, s6, s8
	s_nop 0
	v_addc_co_u32_e32 v41, vcc, 0, v33, vcc
	v_add_co_u32_e32 v42, vcc, s36, v32
	s_addc_u32 s7, s7, s9
	s_nop 0
	v_addc_co_u32_e32 v43, vcc, 0, v33, vcc
	v_add_co_u32_e32 v70, vcc, s37, v32
	s_add_u32 s0, s0, s10
	s_nop 0
	v_addc_co_u32_e32 v71, vcc, 0, v33, vcc
	v_add_co_u32_e32 v32, vcc, s38, v32
	s_addc_u32 s1, s1, s11
	s_nop 0
	v_addc_co_u32_e32 v33, vcc, 0, v33, vcc
	v_add_co_u32_e32 v20, vcc, s35, v20
	s_add_u32 s12, s12, s14
	s_nop 0
	v_addc_co_u32_e32 v21, vcc, 0, v21, vcc
	s_addc_u32 s13, s13, s15
	s_cmpk_gt_i32 s72, 0x1fff
	s_waitcnt vmcnt(11)
	v_lshlrev_b32_e32 v24, 16, v46
	v_and_b32_e32 v25, 0xffff0000, v46
	v_lshlrev_b32_e32 v36, 16, v47
	v_and_b32_e32 v37, 0xffff0000, v47
	s_waitcnt vmcnt(10)
	v_lshlrev_b32_e32 v46, 16, v48
	v_and_b32_e32 v47, 0xffff0000, v48
	v_lshlrev_b32_e32 v48, 16, v49
	v_and_b32_e32 v49, 0xffff0000, v49
	s_waitcnt vmcnt(9)
	v_lshlrev_b32_e32 v54, 16, v50
	v_and_b32_e32 v55, 0xffff0000, v50
	v_lshlrev_b32_e32 v50, 16, v51
	v_and_b32_e32 v51, 0xffff0000, v51
	s_waitcnt vmcnt(7)
	v_lshlrev_b32_e32 v58, 16, v72
	v_and_b32_e32 v59, 0xffff0000, v72
	v_lshlrev_b32_e32 v60, 16, v73
	v_and_b32_e32 v61, 0xffff0000, v73
	s_waitcnt vmcnt(5)
	v_lshlrev_b32_e32 v80, 16, v76
	v_and_b32_e32 v81, 0xffff0000, v76
	v_lshlrev_b32_e32 v76, 16, v77
	v_and_b32_e32 v77, 0xffff0000, v77
	v_pk_mul_f32 v[24:25], v[30:31], v[24:25] op_sel_hi:[0,1]
	v_pk_mul_f32 v[36:37], v[30:31], v[36:37] op_sel_hi:[0,1]
	v_lshlrev_b32_e32 v56, 16, v52
	v_and_b32_e32 v57, 0xffff0000, v52
	v_lshlrev_b32_e32 v52, 16, v53
	v_and_b32_e32 v53, 0xffff0000, v53
	v_lshlrev_b32_e32 v72, 16, v74
	v_and_b32_e32 v73, 0xffff0000, v74
	v_lshlrev_b32_e32 v74, 16, v75
	v_and_b32_e32 v75, 0xffff0000, v75
	s_waitcnt vmcnt(4)
	v_lshlrev_b32_e32 v82, 16, v78
	v_and_b32_e32 v83, 0xffff0000, v78
	v_lshlrev_b32_e32 v78, 16, v79
	v_and_b32_e32 v79, 0xffff0000, v79
	v_pk_mul_f32 v[54:55], v[30:31], v[54:55] op_sel_hi:[0,1]
	v_pk_mul_f32 v[50:51], v[30:31], v[50:51] op_sel_hi:[0,1]
	v_pk_mul_f32 v[58:59], v[30:31], v[58:59] op_sel_hi:[0,1]
	v_pk_mul_f32 v[60:61], v[30:31], v[60:61] op_sel_hi:[0,1]
	v_pk_mul_f32 v[80:81], v[30:31], v[80:81] op_sel_hi:[0,1]
	v_pk_mul_f32 v[76:77], v[30:31], v[76:77] op_sel_hi:[0,1]
	s_waitcnt vmcnt(3)
	v_pk_fma_f32 v[4:5], v[4:5], v[36:37], v[48:49]
	v_pk_fma_f32 v[2:3], v[2:3], v[24:25], v[46:47]
	s_waitcnt vmcnt(2)
	v_pk_fma_f32 v[8:9], v[8:9], v[50:51], v[52:53]
	v_pk_fma_f32 v[6:7], v[6:7], v[54:55], v[56:57]
	s_waitcnt vmcnt(1)
	v_pk_fma_f32 v[12:13], v[12:13], v[60:61], v[74:75]
	v_pk_fma_f32 v[10:11], v[10:11], v[58:59], v[72:73]
	s_waitcnt vmcnt(0)
	v_pk_fma_f32 v[16:17], v[16:17], v[76:77], v[78:79]
	v_pk_fma_f32 v[14:15], v[14:15], v[80:81], v[82:83]
	global_store_dwordx4 v[28:29], v[2:5], off offset:-4096
	global_store_dwordx4 v[38:39], v[6:9], off offset:1024
	global_store_dwordx4 v[38:39], v[10:13], off offset:2048
	global_store_dwordx4 v[38:39], v[14:17], off offset:3072
	global_load_dwordx2 v[24:25], v[22:23], off
	global_load_dwordx2 v[36:37], v[62:63], off
	global_load_dwordx2 v[38:39], v[22:23], off offset:512
	global_load_dwordx2 v[46:47], v[64:65], off
	global_load_dwordx2 v[48:49], v[22:23], off offset:1024
	global_load_dwordx2 v[50:51], v[66:67], off
	global_load_dwordx2 v[52:53], v[22:23], off offset:1536
	global_load_dwordx2 v[54:55], v[68:69], off
	global_load_dwordx4 v[2:5], v[26:27], off nt
	global_load_dwordx4 v[6:9], v[26:27], off offset:1024 nt
	global_load_dwordx4 v[10:13], v[26:27], off offset:2048 nt
	global_load_dwordx4 v[14:17], v[26:27], off offset:3072 nt
	s_waitcnt vmcnt(11)
	v_lshlrev_b32_e32 v26, 16, v24
	v_and_b32_e32 v27, 0xffff0000, v24
	v_lshlrev_b32_e32 v24, 16, v25
	v_and_b32_e32 v25, 0xffff0000, v25
	s_waitcnt vmcnt(10)
	v_lshlrev_b32_e32 v56, 16, v36
	v_and_b32_e32 v57, 0xffff0000, v36
	v_lshlrev_b32_e32 v36, 16, v37
	v_and_b32_e32 v37, 0xffff0000, v37
	s_waitcnt vmcnt(9)
	v_lshlrev_b32_e32 v58, 16, v38
	v_and_b32_e32 v59, 0xffff0000, v38
	v_lshlrev_b32_e32 v38, 16, v39
	v_and_b32_e32 v39, 0xffff0000, v39
	s_waitcnt vmcnt(7)
	v_lshlrev_b32_e32 v62, 16, v48
	v_and_b32_e32 v63, 0xffff0000, v48
	v_lshlrev_b32_e32 v48, 16, v49
	v_and_b32_e32 v49, 0xffff0000, v49
	s_waitcnt vmcnt(5)
	v_lshlrev_b32_e32 v66, 16, v52
	v_and_b32_e32 v67, 0xffff0000, v52
	v_lshlrev_b32_e32 v52, 16, v53
	v_and_b32_e32 v53, 0xffff0000, v53
	v_pk_mul_f32 v[26:27], v[30:31], v[26:27] op_sel_hi:[0,1]
	v_pk_mul_f32 v[24:25], v[30:31], v[24:25] op_sel_hi:[0,1]
	v_lshlrev_b32_e32 v60, 16, v46
	v_and_b32_e32 v61, 0xffff0000, v46
	v_lshlrev_b32_e32 v46, 16, v47
	v_and_b32_e32 v47, 0xffff0000, v47
	v_lshlrev_b32_e32 v64, 16, v50
	v_and_b32_e32 v65, 0xffff0000, v50
	v_lshlrev_b32_e32 v50, 16, v51
	v_and_b32_e32 v51, 0xffff0000, v51
	s_waitcnt vmcnt(4)
	v_lshlrev_b32_e32 v68, 16, v54
	v_and_b32_e32 v69, 0xffff0000, v54
	v_lshlrev_b32_e32 v54, 16, v55
	v_and_b32_e32 v55, 0xffff0000, v55
	v_pk_mul_f32 v[58:59], v[30:31], v[58:59] op_sel_hi:[0,1]
	v_pk_mul_f32 v[38:39], v[30:31], v[38:39] op_sel_hi:[0,1]
	v_pk_mul_f32 v[62:63], v[30:31], v[62:63] op_sel_hi:[0,1]
	v_pk_mul_f32 v[48:49], v[30:31], v[48:49] op_sel_hi:[0,1]
	v_pk_mul_f32 v[66:67], v[30:31], v[66:67] op_sel_hi:[0,1]
	v_pk_mul_f32 v[52:53], v[30:31], v[52:53] op_sel_hi:[0,1]
	s_waitcnt vmcnt(3)
	v_pk_fma_f32 v[4:5], v[4:5], v[24:25], v[36:37]
	v_pk_fma_f32 v[2:3], v[2:3], v[26:27], v[56:57]
	s_waitcnt vmcnt(2)
	v_pk_fma_f32 v[8:9], v[8:9], v[38:39], v[46:47]
	v_pk_fma_f32 v[6:7], v[6:7], v[58:59], v[60:61]
	s_waitcnt vmcnt(1)
	v_pk_fma_f32 v[12:13], v[12:13], v[48:49], v[50:51]
	v_pk_fma_f32 v[10:11], v[10:11], v[62:63], v[64:65]
	s_waitcnt vmcnt(0)
	v_pk_fma_f32 v[16:17], v[16:17], v[52:53], v[54:55]
	v_pk_fma_f32 v[14:15], v[14:15], v[66:67], v[68:69]
	global_store_dwordx4 v[28:29], v[2:5], off
	global_store_dwordx4 v[28:29], v[6:9], off offset:1024
	global_store_dwordx4 v[28:29], v[10:13], off offset:2048
	global_store_dwordx4 v[28:29], v[14:17], off offset:3072
	global_load_dwordx2 v[24:25], v[22:23], off offset:2048
	global_load_dwordx2 v[26:27], v[40:41], off
	global_load_dwordx2 v[28:29], v[22:23], off offset:2560
	global_load_dwordx2 v[36:37], v[42:43], off
	global_load_dwordx2 v[38:39], v[22:23], off offset:3072
	global_load_dwordx2 v[46:47], v[70:71], off
	global_load_dwordx2 v[48:49], v[22:23], off offset:3584
	global_load_dwordx2 v[50:51], v[32:33], off
	global_load_dwordx4 v[2:5], v[34:35], off nt
	global_load_dwordx4 v[6:9], v[34:35], off offset:1024 nt
	global_load_dwordx4 v[10:13], v[34:35], off offset:2048 nt
	global_load_dwordx4 v[14:17], v[34:35], off offset:3072 nt
	s_waitcnt vmcnt(11)
	v_lshlrev_b32_e32 v22, 16, v24
	v_and_b32_e32 v23, 0xffff0000, v24
	v_lshlrev_b32_e32 v24, 16, v25
	v_and_b32_e32 v25, 0xffff0000, v25
	s_waitcnt vmcnt(10)
	v_lshlrev_b32_e32 v32, 16, v26
	v_and_b32_e32 v33, 0xffff0000, v26
	v_lshlrev_b32_e32 v26, 16, v27
	v_and_b32_e32 v27, 0xffff0000, v27
	s_waitcnt vmcnt(9)
	v_lshlrev_b32_e32 v34, 16, v28
	v_and_b32_e32 v35, 0xffff0000, v28
	v_lshlrev_b32_e32 v28, 16, v29
	v_and_b32_e32 v29, 0xffff0000, v29
	s_waitcnt vmcnt(7)
	v_lshlrev_b32_e32 v42, 16, v38
	v_and_b32_e32 v43, 0xffff0000, v38
	v_lshlrev_b32_e32 v38, 16, v39
	v_and_b32_e32 v39, 0xffff0000, v39
	s_waitcnt vmcnt(5)
	v_lshlrev_b32_e32 v54, 16, v48
	v_and_b32_e32 v55, 0xffff0000, v48
	v_lshlrev_b32_e32 v48, 16, v49
	v_and_b32_e32 v49, 0xffff0000, v49
	v_pk_mul_f32 v[22:23], v[30:31], v[22:23] op_sel_hi:[0,1]
	v_pk_mul_f32 v[24:25], v[30:31], v[24:25] op_sel_hi:[0,1]
	v_lshlrev_b32_e32 v40, 16, v36
	v_and_b32_e32 v41, 0xffff0000, v36
	v_lshlrev_b32_e32 v36, 16, v37
	v_and_b32_e32 v37, 0xffff0000, v37
	v_lshlrev_b32_e32 v52, 16, v46
	v_and_b32_e32 v53, 0xffff0000, v46
	v_lshlrev_b32_e32 v46, 16, v47
	v_and_b32_e32 v47, 0xffff0000, v47
	s_waitcnt vmcnt(4)
	v_lshlrev_b32_e32 v56, 16, v50
	v_and_b32_e32 v57, 0xffff0000, v50
	v_lshlrev_b32_e32 v50, 16, v51
	v_and_b32_e32 v51, 0xffff0000, v51
	v_pk_mul_f32 v[34:35], v[30:31], v[34:35] op_sel_hi:[0,1]
	v_pk_mul_f32 v[28:29], v[30:31], v[28:29] op_sel_hi:[0,1]
	v_pk_mul_f32 v[42:43], v[30:31], v[42:43] op_sel_hi:[0,1]
	v_pk_mul_f32 v[38:39], v[30:31], v[38:39] op_sel_hi:[0,1]
	v_pk_mul_f32 v[54:55], v[30:31], v[54:55] op_sel_hi:[0,1]
	v_pk_mul_f32 v[30:31], v[30:31], v[48:49] op_sel_hi:[0,1]
	s_waitcnt vmcnt(3)
	v_pk_fma_f32 v[4:5], v[4:5], v[24:25], v[26:27]
	v_pk_fma_f32 v[2:3], v[2:3], v[22:23], v[32:33]
	s_waitcnt vmcnt(2)
	v_pk_fma_f32 v[8:9], v[8:9], v[28:29], v[36:37]
	v_pk_fma_f32 v[6:7], v[6:7], v[34:35], v[40:41]
	s_waitcnt vmcnt(1)
	v_pk_fma_f32 v[12:13], v[12:13], v[38:39], v[46:47]
	v_pk_fma_f32 v[10:11], v[10:11], v[42:43], v[52:53]
	s_waitcnt vmcnt(0)
	v_pk_fma_f32 v[16:17], v[16:17], v[30:31], v[50:51]
	v_pk_fma_f32 v[14:15], v[14:15], v[54:55], v[56:57]
	global_store_dwordx4 v[20:21], v[2:5], off
	global_store_dwordx4 v[20:21], v[6:9], off offset:1024
	global_store_dwordx4 v[20:21], v[10:13], off offset:2048
	global_store_dwordx4 v[20:21], v[14:17], off offset:3072
	s_cbranch_scc0 .LBB0_2791
